# weights workspace layout inside each 32KB slot changed to [k-half][256 rows][32 k] so each GEMM k-step DMA reads full 128B lines; narrow gdn a/b product loads batched 16 deep
# speedup vs baseline: 1.0372x; 1.0372x over previous
; DI void lds_barrier() { asm volatile("s_waitcnt lgkmcnt(0)\n\ts_barrier" ::: "memory"); }
; #define ISSUE() do { const int ka_ = (kp + koff >= nk) ? kp + koff - nk : kp + koff; \
;                 glds16x5(A + ka_ * 32, pbt + (size_t)(ka_ >> 1) * 16384 + (ka_ & 1) * 32, va, vb0, vb1, vb2, vb3, lbase + (unsigned)sp * H5_STAGE); \
;                 ++kp; if (kp == nk) { kp = 0; ++tp; pbt += (size_t)512 * K; if (tp == ntw) { tp = 0; pbt = Bt; } } sp = (sp == 2) ? 0 : sp + 1; } while (0)
; DI void run_jobs(const Params& P, int rb, int jj_lo, int jj_hi, unsigned char* smem) {
;     ...
;             const int nk = K >> 5, nk64 = K >> 6, ntw = nt >> 1, S = ntw * nk;
;             const int drow = tid >> 2, kcs = (tid & 3) ^ ((4 - ((tid >> 4) & 3)) & 3);
;             const unsigned va = (unsigned)((drow * lda + kcs * 8) * 2);
;             const unsigned vb0 = (unsigned)((drow * 64 + kcs * 8) * 2), vb1 = vb0 + 16384u;
;             const unsigned vb2 = vb0 + (unsigned)nk64 * 32768u, vb3 = vb2 + 16384u;
;             const unsigned lbase = (unsigned)(size_t)smem + (unsigned)__builtin_amdgcn_readfirstlane(wid) * 1024u;
;             const int r16 = lane & 15, q4 = lane >> 4;
;             const int ko = ((q4 ^ ((4 - (r16 >> 2)) & 3)) << 4);
;             const int fa = (wm * 64 + r16) * 64 + ko, fb = H5_A + (wn * 128 + r16) * 64 + ko;
;             f32x4 acc[4][8];
; #pragma unroll
;             for (int i = 0; i < 4; ++i)
; #pragma unroll
;                 for (int jq = 0; jq < 8; ++jq) acc[i][jq] = (f32x4){0.f, 0.f, 0.f, 0.f};
;             const int toff = (int)((blockIdx.x & 7u) * (unsigned)ntw) >> 3;
;             const int koff = (int)((blockIdx.x >> 3) * (unsigned)nk) >> 5;
;             int kp = 0, sp = 0, tp = toff;
;             const bf16_t* pbt = Bt + (size_t)toff * 512 * K;
;     ...
;             ISSUE();
;             ISSUE();
;             ISSUE();
;             asm volatile("s_waitcnt vmcnt(10)" ::: "memory");
;             lds_barrier();
.LBB0_138:
	v_readlane_b32 s64, v249, 53
	s_cmp_eq_u32 s34, 1
	v_readlane_b32 s65, v249, 54
	v_readlane_b32 s36, v250, 58
	s_cselect_b32 s59, s65, s89
	s_cselect_b32 s62, s64, s88
	v_cndmask_b32_e64 v184, 0.5, 1.0, s[6:7]
	s_lshl_b64 s[6:7], s[4:5], 12
	v_readlane_b32 s50, v249, 8
	v_readlane_b32 s51, v249, 9
	s_add_u32 s16, s50, s6
	s_addc_u32 s17, s51, s7
	s_lshl_b32 s19, s4, 2
	s_add_i32 s4, s15, -3
	s_ashr_i32 s4, s4, 1
	s_add_i32 s6, s4, s19
	s_ashr_i32 s7, s6, 31
	s_lshl_b64 s[6:7], s[6:7], 10
	s_and_b64 s[8:9], s[80:81], exec
	s_cselect_b32 s7, s7, 0
	s_cselect_b32 s6, s6, 0
	v_readfirstlane_b32 s4, v178
	v_readlane_b32 s68, v249, 57
	s_lshr_b32 s52, s20, 5
	s_lshl_b32 s8, s20, 9
	s_lshl_b32 s55, s4, 10
	s_lshl_b64 s[6:7], s[6:7], 2
	v_readlane_b32 s69, v249, 58
	v_readlane_b32 s37, v250, 59
	s_add_u32 s36, s68, s6
	v_readlane_b32 s70, v249, 59
	s_addc_u32 s37, s69, s7
	v_readlane_b32 s71, v249, 60
	s_add_u32 s6, s70, s6
	s_addc_u32 s7, s71, s7
	v_ashrrev_i32_e32 v0, 2, v182
	s_movk_i32 s4, 0xffc0
	s_cmp_lg_u32 0, -1
	v_mul_lo_u32 v3, s20, v0
	v_lshlrev_b32_e32 v4, 6, v0
	v_and_or_b32 v0, v0, s4, v180
	s_cselect_b32 s4, 0, 0
	s_add_i32 s55, s55, s4
	v_readlane_b32 s4, v250, 10
	s_mul_i32 s4, s22, s4
	s_lshr_b32 s56, s4, 3
	v_readlane_b32 s4, v250, 11
	s_mul_i32 s4, s52, s4
	s_ashr_i32 s57, s4, 5
	s_mul_i32 s4, s8, s56
	s_lshl_b64 s[20:21], s[4:5], 1
	s_add_u32 s4, s94, s20
	s_addc_u32 s58, s95, s21
	s_cmp_ge_i32 s57, s52
	s_cselect_b32 s9, s52, 0
	s_sub_i32 s9, s57, s9
	s_lshl_b32 s20, s9, 5
	s_ashr_i32 s21, s20, 31
	s_lshl_b64 s[20:21], s[20:21], 1
	s_add_u32 s20, s28, s20
	v_lshrrev_b32_e32 v2, 4, v182
	s_addc_u32 s21, s29, s21
	s_ashr_i32 s60, s9, 1
	v_sub_u32_e32 v2, 0, v2
	s_ashr_i32 s61, s60, 31
	v_xor_b32_e32 v2, v182, v2
	s_lshl_b64 s[60:61], s[60:61], 15
	v_lshlrev_b32_e32 v2, 3, v2
	s_add_u32 s60, s4, s60
	v_and_b32_e32 v2, 24, v2
	s_addc_u32 s61, s58, s61
	s_lshl_b32 s9, s9, 14
	v_lshl_or_b32 v237, v2, 1, v4
	s_and_b32 s9, s9, 0x4000
	v_or_b32_e32 v3, v3, v2
	v_add_u32_e32 v238, s8, v237
	s_add_u32 s60, s60, s9
	v_lshlrev_b32_e32 v239, 1, v3
	v_add_u32_e32 v240, 0x2000, v237
	v_add_u32_e32 v241, 0x2000, v238
	s_addc_u32 s61, s61, 0
	s_mov_b32 s9, m0
	s_mov_b32 m0, s55
	s_nop 0
	global_load_lds_dwordx4 v239, s[20:21]
	s_add_u32 m0, m0, 0x2000
	s_nop 0
	global_load_lds_dwordx4 v237, s[60:61]
	s_add_u32 m0, m0, 0x2000
	s_nop 0
	global_load_lds_dwordx4 v240, s[60:61]
	s_add_u32 m0, m0, 0x2000
	s_nop 0
	global_load_lds_dwordx4 v238, s[60:61]
	s_add_u32 m0, m0, 0x2000
	s_nop 0
	global_load_lds_dwordx4 v241, s[60:61]
	s_mov_b32 m0, s9
	s_add_i32 s9, s57, 1
	s_cmp_ge_i32 s9, s52
	s_cselect_b32 s20, s52, 0
	s_sub_i32 s9, s9, s20
	s_lshl_b32 s20, s9, 5
	s_ashr_i32 s21, s20, 31
	s_lshl_b64 s[20:21], s[20:21], 1
	s_add_u32 s20, s28, s20
	s_addc_u32 s21, s29, s21
	s_ashr_i32 s60, s9, 1
	s_ashr_i32 s61, s60, 31
	s_lshl_b64 s[60:61], s[60:61], 15
	s_add_u32 s60, s4, s60
	s_addc_u32 s61, s58, s61
	s_lshl_b32 s9, s9, 14
	s_and_b32 s9, s9, 0x4000
	s_add_u32 s60, s60, s9
	s_addc_u32 s61, s61, 0
	s_add_i32 s9, s55, 0xa000
	s_mov_b32 s63, m0
	s_mov_b32 m0, s9
	s_nop 0
	global_load_lds_dwordx4 v239, s[20:21]
	s_add_u32 m0, m0, 0x2000
	s_nop 0
	global_load_lds_dwordx4 v237, s[60:61]
	s_add_u32 m0, m0, 0x2000
	s_nop 0
	global_load_lds_dwordx4 v240, s[60:61]
	s_add_u32 m0, m0, 0x2000
	s_nop 0
	global_load_lds_dwordx4 v238, s[60:61]
	s_add_u32 m0, m0, 0x2000
	s_nop 0
	global_load_lds_dwordx4 v241, s[60:61]
	s_mov_b32 m0, s63
	s_add_i32 s9, s57, 2
	s_cmp_ge_i32 s9, s52
	s_cselect_b32 s20, s52, 0
	s_sub_i32 s9, s9, s20
	s_lshl_b32 s20, s9, 5
	s_ashr_i32 s21, s20, 31
	s_lshl_b64 s[20:21], s[20:21], 1
	s_add_u32 s20, s28, s20
	s_addc_u32 s21, s29, s21
	s_ashr_i32 s60, s9, 1
	s_ashr_i32 s61, s60, 31
	s_lshl_b64 s[60:61], s[60:61], 15
	s_add_u32 s60, s4, s60
	s_addc_u32 s61, s58, s61
	s_lshl_b32 s9, s9, 14
	s_and_b32 s9, s9, 0x4000
	s_add_u32 s60, s60, s9
	v_lshrrev_b32_e32 v2, 2, v182
	s_addc_u32 s61, s61, 0
	s_add_i32 s9, s55, 0x14000
	s_mov_b32 s63, m0
	s_mov_b32 m0, s9
	s_nop 0
	global_load_lds_dwordx4 v239, s[20:21]
	s_add_u32 m0, m0, 0x2000
	s_nop 0
	global_load_lds_dwordx4 v237, s[60:61]
	s_add_u32 m0, m0, 0x2000
	s_nop 0
	global_load_lds_dwordx4 v240, s[60:61]
	s_add_u32 m0, m0, 0x2000
	s_nop 0
	global_load_lds_dwordx4 v238, s[60:61]
	s_add_u32 m0, m0, 0x2000
	s_nop 0
	global_load_lds_dwordx4 v241, s[60:61]
	s_mov_b32 m0, s63
	v_readlane_b32 s20, v248, 57
	v_bfe_u32 v4, v182, 4, 2
	v_sub_u32_e32 v2, 0, v2
	v_readlane_b32 s21, v248, 58
	v_readlane_b32 s72, v249, 61
	v_bitop3_b32 v5, v4, v2, 3 bitop3:0x78
	s_lshl_b64 s[20:21], s[20:21], 2
	v_readlane_b32 s73, v249, 62
	v_and_b32_e32 v1, 3, v178
	v_lshlrev_b32_e32 v242, 4, v5
	v_lshlrev_b32_e32 v183, 2, v4
	s_add_u32 s72, s62, s20
	v_mov_b64_e32 v[4:5], s[30:31]
	s_movk_i32 s9, 0x1600
	v_lshlrev_b32_e32 v2, 7, v1
	s_addc_u32 s73, s59, s21
	v_mad_i64_i32 v[4:5], s[20:21], v0, s9, v[4:5]
	v_mov_b32_e32 v3, v177
	v_and_b32_e32 v176, 48, v182
	v_lshl_add_u64 v[4:5], v[4:5], 0, v[2:3]
	v_lshlrev_b32_e32 v6, 1, v176
	v_mov_b32_e32 v7, v177
	v_lshlrev_b32_e32 v10, 1, v0
	v_lshl_add_u64 v[188:189], v[4:5], 0, v[6:7]
	v_or_b32_e32 v4, 16, v0
	v_ashrrev_i32_e32 v11, 31, v10
	v_lshl_add_u64 v[200:201], v[10:11], 2, s[96:97]
	v_lshlrev_b32_e32 v10, 1, v4
	v_or_b32_e32 v6, 32, v0
	v_ashrrev_i32_e32 v11, 31, v10
	v_lshl_add_u64 v[204:205], v[10:11], 2, s[96:97]
	v_lshlrev_b32_e32 v10, 1, v6
	v_or_b32_e32 v1, v2, v180
	s_waitcnt vmcnt(10)
	v_or_b32_e32 v8, 48, v0
	v_ashrrev_i32_e32 v11, 31, v10
	v_lshlrev_b32_e32 v244, 6, v1
	s_waitcnt lgkmcnt(0)
	s_barrier
; DI void lds_barrier() { asm volatile("s_waitcnt lgkmcnt(0)\n\ts_barrier" ::: "memory"); }
; #define ISSUE() do { const int ka_ = (kp + koff >= nk) ? kp + koff - nk : kp + koff; \
;                 glds16x5(A + ka_ * 32, pbt + (size_t)(ka_ >> 1) * 16384 + (ka_ & 1) * 32, va, vb0, vb1, vb2, vb3, lbase + (unsigned)sp * H5_STAGE); \
;                 ++kp; if (kp == nk) { kp = 0; ++tp; pbt += (size_t)512 * K; if (tp == ntw) { tp = 0; pbt = Bt; } } sp = (sp == 2) ? 0 : sp + 1; } while (0)
; DI void run_jobs(const Params& P, int rb, int jj_lo, int jj_hi, unsigned char* smem) {
;     ...
;             const int r16 = lane & 15, q4 = lane >> 4;
;             const int ko = ((q4 ^ ((4 - (r16 >> 2)) & 3)) << 4);
;             const int fa = (wm * 64 + r16) * 64 + ko, fb = H5_A + (wn * 128 + r16) * 64 + ko;
;             f32x4 acc[4][8];
; #pragma unroll
;             for (int i = 0; i < 4; ++i)
; #pragma unroll
;                 for (int jq = 0; jq < 8; ++jq) acc[i][jq] = (f32x4){0.f, 0.f, 0.f, 0.f};
;             const int toff = (int)((blockIdx.x & 7u) * (unsigned)ntw) >> 3;
;             const int koff = (int)((blockIdx.x >> 3) * (unsigned)nk) >> 5;
;             int kp = 0, sp = 0, tp = toff;
;             const bf16_t* pbt = Bt + (size_t)toff * 512 * K;
;     ...
;             ISSUE();
;             ISSUE();
;             ISSUE();
;             asm volatile("s_waitcnt vmcnt(10)" ::: "memory");
;             lds_barrier();
;             int kt = 0, t = toff, st = 0;
	v_ashrrev_i32_e32 v1, 31, v0
	v_lshl_add_u64 v[208:209], v[10:11], 2, s[96:97]
	v_lshlrev_b32_e32 v10, 1, v8
	v_readlane_b32 s67, v249, 56
	v_readlane_b32 s74, v249, 63
	v_readlane_b32 s75, v248, 0
	v_readlane_b32 s76, v248, 1
	v_readlane_b32 s78, v248, 3
	v_readlane_b32 s79, v248, 4
	v_lshlrev_b32_e32 v243, 6, v0
	v_mad_i64_i32 v[190:191], s[20:21], v0, s33, 0
	v_ashrrev_i32_e32 v5, 31, v4
	v_mad_i64_i32 v[192:193], s[20:21], v4, s33, 0
	v_ashrrev_i32_e32 v7, 31, v6
	v_mad_i64_i32 v[194:195], s[20:21], v6, s33, 0
	v_ashrrev_i32_e32 v9, 31, v8
	v_mad_i64_i32 v[196:197], s[20:21], v8, s33, 0
	v_lshlrev_b64 v[198:199], 10, v[0:1]
	v_ashrrev_i32_e32 v11, 31, v10
	v_lshlrev_b64 v[214:215], 11, v[0:1]
	v_mov_b32_e32 v0, 0
	s_mov_b32 s53, 3
	s_mov_b32 s23, 0
	s_mul_i32 s54, s52, s22
	v_mov_b32_e32 v186, v184
	v_mov_b32_e32 v187, v184
	v_lshlrev_b64 v[202:203], 10, v[4:5]
	v_lshlrev_b64 v[206:207], 10, v[6:7]
	v_lshlrev_b64 v[210:211], 10, v[8:9]
	v_lshl_add_u64 v[212:213], v[10:11], 2, s[96:97]
	v_lshlrev_b64 v[216:217], 11, v[4:5]
	v_lshlrev_b64 v[218:219], 11, v[6:7]
	v_lshlrev_b64 v[220:221], 11, v[8:9]
	v_or_b32_e32 v246, v2, v183
	s_lshl_b32 s59, s8, 1
	s_mov_b32 s20, 0
	s_mov_b32 s62, s56
	s_mov_b32 s60, 0
	s_mov_b32 s61, 0
	v_mov_b32_e32 v1, v0
	v_mov_b32_e32 v2, v0
	v_mov_b32_e32 v3, v0
	v_mov_b32_e32 v4, v0
	v_mov_b32_e32 v5, v0
	v_mov_b32_e32 v6, v0
	v_mov_b32_e32 v7, v0
	v_mov_b32_e32 v8, v0
	v_mov_b32_e32 v9, v0
	v_mov_b32_e32 v10, v0
	v_mov_b32_e32 v11, v0
	v_mov_b32_e32 v12, v0
	v_mov_b32_e32 v13, v0
	v_mov_b32_e32 v14, v0
	v_mov_b32_e32 v15, v0
	v_mov_b32_e32 v16, v0
	v_mov_b32_e32 v17, v0
	v_mov_b32_e32 v18, v0
	v_mov_b32_e32 v19, v0
	v_mov_b32_e32 v20, v0
	v_mov_b32_e32 v21, v0
	v_mov_b32_e32 v22, v0
	v_mov_b32_e32 v23, v0
	v_mov_b32_e32 v24, v0
	v_mov_b32_e32 v25, v0
	v_mov_b32_e32 v26, v0
	v_mov_b32_e32 v27, v0
	v_mov_b32_e32 v28, v0
	v_mov_b32_e32 v29, v0
	v_mov_b32_e32 v30, v0
	v_mov_b32_e32 v31, v0
	v_mov_b32_e32 v32, v0
	v_mov_b32_e32 v33, v0
	v_mov_b32_e32 v34, v0
	v_mov_b32_e32 v35, v0
	v_mov_b32_e32 v36, v0
	v_mov_b32_e32 v37, v0
	v_mov_b32_e32 v38, v0
	v_mov_b32_e32 v39, v0
	v_mov_b32_e32 v40, v0
	v_mov_b32_e32 v41, v0
	v_mov_b32_e32 v42, v0
	v_mov_b32_e32 v43, v0
	v_mov_b32_e32 v44, v0
	v_mov_b32_e32 v45, v0
	v_mov_b32_e32 v46, v0
	v_mov_b32_e32 v47, v0
	v_mov_b32_e32 v48, v0
	v_mov_b32_e32 v49, v0
	v_mov_b32_e32 v50, v0
	v_mov_b32_e32 v51, v0
	v_mov_b32_e32 v52, v0
	v_mov_b32_e32 v53, v0
	v_mov_b32_e32 v54, v0
	v_mov_b32_e32 v55, v0
	v_mov_b32_e32 v56, v0
	v_mov_b32_e32 v57, v0
	v_mov_b32_e32 v58, v0
	v_mov_b32_e32 v59, v0
	v_mov_b32_e32 v60, v0
	v_mov_b32_e32 v61, v0
	v_mov_b32_e32 v62, v0
	v_mov_b32_e32 v63, v0
	v_mov_b32_e32 v64, v0
	v_mov_b32_e32 v65, v0
	v_mov_b32_e32 v66, v0
	v_mov_b32_e32 v67, v0
	v_mov_b32_e32 v68, v0
	v_mov_b32_e32 v69, v0
	v_mov_b32_e32 v70, v0
	v_mov_b32_e32 v71, v0
	v_mov_b32_e32 v72, v0
	v_mov_b32_e32 v73, v0
	v_mov_b32_e32 v74, v0
	v_mov_b32_e32 v75, v0
	v_mov_b32_e32 v76, v0
	v_mov_b32_e32 v77, v0
	v_mov_b32_e32 v78, v0
	v_mov_b32_e32 v79, v0
	v_mov_b32_e32 v80, v0
	v_mov_b32_e32 v81, v0
	v_mov_b32_e32 v82, v0
	v_mov_b32_e32 v83, v0
	v_mov_b32_e32 v84, v0
	v_mov_b32_e32 v85, v0
	v_mov_b32_e32 v86, v0
	v_mov_b32_e32 v87, v0
	v_mov_b32_e32 v88, v0
	v_mov_b32_e32 v89, v0
	v_mov_b32_e32 v90, v0
	v_mov_b32_e32 v91, v0
	v_mov_b32_e32 v92, v0
	v_mov_b32_e32 v93, v0
	v_mov_b32_e32 v94, v0
	v_mov_b32_e32 v95, v0
	v_mov_b32_e32 v96, v0
	v_mov_b32_e32 v97, v0
	v_mov_b32_e32 v98, v0
	v_mov_b32_e32 v99, v0
	v_mov_b32_e32 v100, v0
	v_mov_b32_e32 v101, v0
	v_mov_b32_e32 v102, v0
	v_mov_b32_e32 v103, v0
	v_mov_b32_e32 v104, v0
	v_mov_b32_e32 v105, v0
	v_mov_b32_e32 v106, v0
	v_mov_b32_e32 v107, v0
	v_mov_b32_e32 v108, v0
	v_mov_b32_e32 v109, v0
	v_mov_b32_e32 v110, v0
	v_mov_b32_e32 v111, v0
	v_mov_b32_e32 v112, v0
	v_mov_b32_e32 v113, v0
	v_mov_b32_e32 v114, v0
	v_mov_b32_e32 v115, v0
	v_mov_b32_e32 v116, v0
	v_mov_b32_e32 v117, v0
	v_mov_b32_e32 v118, v0
	v_mov_b32_e32 v119, v0
	v_mov_b32_e32 v120, v0
	v_mov_b32_e32 v121, v0
	v_mov_b32_e32 v122, v0
	v_mov_b32_e32 v123, v0
	v_mov_b32_e32 v124, v0
	v_mov_b32_e32 v125, v0
	v_mov_b32_e32 v126, v0
	v_mov_b32_e32 v127, v0
	v_and_b32_e32 v245, 63, v182
	s_mov_b64 s[68:69], s[0:1]
	s_mov_b64 s[70:71], s[24:25]
	s_movk_i32 s67, 0xfa00
	s_movk_i32 s74, 0x3000
	s_movk_i32 s75, 0xc00
	s_mov_b32 s76, 0x1e000
	s_mov_b32 s78, 0xe000
	s_mov_b32 s79, 0x13000
	s_mov_b32 s0, 0x2c000
	v_readlane_b32 s66, v249, 55
	v_readlane_b32 s77, v248, 2
	v_readlane_b32 s38, v250, 60
	v_readlane_b32 s39, v250, 61
	v_readlane_b32 s40, v250, 62
	v_readlane_b32 s41, v250, 63
	v_readlane_b32 s42, v249, 0
	v_readlane_b32 s43, v249, 1
	v_readlane_b32 s44, v249, 2
	v_readlane_b32 s45, v249, 3
	v_readlane_b32 s46, v249, 4
	v_readlane_b32 s47, v249, 5
	v_readlane_b32 s48, v249, 6
	v_readlane_b32 s49, v249, 7
	s_branch .LBB0_142

; DI void lds_barrier() { asm volatile("s_waitcnt lgkmcnt(0)\n\ts_barrier" ::: "memory"); }
; #define ISSUE() do { const int ka_ = (kp + koff >= nk) ? kp + koff - nk : kp + koff; \
;                 glds16x5(A + ka_ * 32, pbt + (size_t)(ka_ >> 1) * 16384 + (ka_ & 1) * 32, va, vb0, vb1, vb2, vb3, lbase + (unsigned)sp * H5_STAGE); \
;                 ++kp; if (kp == nk) { kp = 0; ++tp; pbt += (size_t)512 * K; if (tp == ntw) { tp = 0; pbt = Bt; } } sp = (sp == 2) ? 0 : sp + 1; } while (0)
; DI void run_jobs(const Params& P, int rb, int jj_lo, int jj_hi, unsigned char* smem) {
;     ...
; #pragma unroll
;                 for (int mt = 0; mt < 4; ++mt)
; #pragma unroll
;                     for (int n_ = 0; n_ < 8; ++n_) acc[mt][n_] = __builtin_amdgcn_mfma_f32_16x16x32_bf16(bfr[n_], af[mt], acc[mt][n_], 0, 0, 0);
;                 if (s + 2 < S) asm volatile("s_waitcnt vmcnt(5)" ::: "memory");
;                 else asm volatile("s_waitcnt vmcnt(0)" ::: "memory");
;                 lds_barrier();
;                 if (s + 3 < S) ISSUE();
;                 st = (st == 2) ? 0 : st + 1;
;                 ++kt;
.LBB0_144:
	s_cmp_eq_u32 s61, 0
	s_cbranch_scc1 .Lg_plain
	s_add_i32 s21, s61, 2
	s_cmp_ge_u32 s21, s54
	s_cbranch_scc1 .Lg_plain
	s_add_i32 s8, s53, s57
	s_cmp_ge_i32 s8, s52
	s_cselect_b32 s9, s52, 0
	s_sub_i32 s21, s8, s9
	s_lshl_b32 s8, s21, 5
	s_ashr_i32 s9, s8, 31
	s_lshl_b64 s[8:9], s[8:9], 1
	s_add_u32 s8, s28, s8
	s_addc_u32 s9, s29, s9
	s_ashr_i32 s64, s21, 1
	s_ashr_i32 s65, s64, 31
	s_lshl_b64 s[64:65], s[64:65], 15
	s_add_u32 s63, s4, s64
	s_addc_u32 s65, s58, s65
	s_lshl_b32 s21, s21, 14
	s_and_b32 s21, s21, 0x4000
	s_add_u32 s64, s63, s21
	s_mul_i32 s21, s23, 0xa000
	s_addc_u32 s65, s65, 0
	s_add_i32 s21, s21, s55
	s_mov_b32 m0, s21
	s_waitcnt lgkmcnt(10)
	v_mfma_f32_16x16x32_bf16 v[124:127], v[140:143], v[172:175], v[124:127]
	s_waitcnt lgkmcnt(9)
	v_mfma_f32_16x16x32_bf16 v[120:123], v[144:147], v[172:175], v[120:123]
	s_waitcnt lgkmcnt(8)
	v_mfma_f32_16x16x32_bf16 v[116:119], v[148:151], v[172:175], v[116:119]
	s_waitcnt lgkmcnt(7)
	v_mfma_f32_16x16x32_bf16 v[112:115], v[152:155], v[172:175], v[112:115]
	s_waitcnt lgkmcnt(6)
	v_mfma_f32_16x16x32_bf16 v[108:111], v[156:159], v[172:175], v[108:111]
	s_waitcnt lgkmcnt(5)
	v_mfma_f32_16x16x32_bf16 v[104:107], v[160:163], v[172:175], v[104:107]
	s_waitcnt lgkmcnt(4)
	v_mfma_f32_16x16x32_bf16 v[100:103], v[164:167], v[172:175], v[100:103]
	s_waitcnt lgkmcnt(3)
	v_mfma_f32_16x16x32_bf16 v[96:99], v[132:135], v[172:175], v[96:99]
	global_load_lds_dwordx4 v239, s[8:9]
	s_add_u32 m0, m0, 0x2000
	s_waitcnt lgkmcnt(2)
	v_mfma_f32_16x16x32_bf16 v[92:95], v[140:143], v[168:171], v[92:95]
	v_mfma_f32_16x16x32_bf16 v[88:91], v[144:147], v[168:171], v[88:91]
	v_mfma_f32_16x16x32_bf16 v[84:87], v[148:151], v[168:171], v[84:87]
	v_mfma_f32_16x16x32_bf16 v[80:83], v[152:155], v[168:171], v[80:83]
	global_load_lds_dwordx4 v237, s[64:65]
	s_add_u32 m0, m0, 0x2000
	v_mfma_f32_16x16x32_bf16 v[76:79], v[156:159], v[168:171], v[76:79]
	v_mfma_f32_16x16x32_bf16 v[72:75], v[160:163], v[168:171], v[72:75]
	v_mfma_f32_16x16x32_bf16 v[68:71], v[164:167], v[168:171], v[68:71]
	v_mfma_f32_16x16x32_bf16 v[64:67], v[132:135], v[168:171], v[64:67]
	global_load_lds_dwordx4 v240, s[64:65]
	s_add_u32 m0, m0, 0x2000
	s_waitcnt lgkmcnt(1)
	v_mfma_f32_16x16x32_bf16 v[60:63], v[140:143], v[136:139], v[60:63]
	v_mfma_f32_16x16x32_bf16 v[56:59], v[144:147], v[136:139], v[56:59]
	v_mfma_f32_16x16x32_bf16 v[52:55], v[148:151], v[136:139], v[52:55]
	v_mfma_f32_16x16x32_bf16 v[48:51], v[152:155], v[136:139], v[48:51]
	global_load_lds_dwordx4 v238, s[64:65]
	s_add_u32 m0, m0, 0x2000
	v_mfma_f32_16x16x32_bf16 v[44:47], v[156:159], v[136:139], v[44:47]
	v_mfma_f32_16x16x32_bf16 v[40:43], v[160:163], v[136:139], v[40:43]
	v_mfma_f32_16x16x32_bf16 v[36:39], v[164:167], v[136:139], v[36:39]
	v_mfma_f32_16x16x32_bf16 v[32:35], v[132:135], v[136:139], v[32:35]
	global_load_lds_dwordx4 v241, s[64:65]
	s_waitcnt lgkmcnt(0)
	v_mfma_f32_16x16x32_bf16 v[28:31], v[140:143], v[128:131], v[28:31]
	v_mfma_f32_16x16x32_bf16 v[24:27], v[144:147], v[128:131], v[24:27]
	v_mfma_f32_16x16x32_bf16 v[20:23], v[148:151], v[128:131], v[20:23]
	v_mfma_f32_16x16x32_bf16 v[16:19], v[152:155], v[128:131], v[16:19]
	v_mfma_f32_16x16x32_bf16 v[12:15], v[156:159], v[128:131], v[12:15]
	v_mfma_f32_16x16x32_bf16 v[8:11], v[160:163], v[128:131], v[8:11]
	v_mfma_f32_16x16x32_bf16 v[4:7], v[164:167], v[128:131], v[4:7]
	v_mfma_f32_16x16x32_bf16 v[0:3], v[132:135], v[128:131], v[0:3]
	s_add_i32 s21, s53, 1
	s_cmp_eq_u32 s21, s52
	s_cselect_b64 s[8:9], -1, 0
	s_add_i32 s53, s56, 1
	s_add_u32 s63, s4, s59
	s_addc_u32 s66, s58, 0
	s_cmp_eq_u32 s53, s22
	s_cselect_b64 s[64:65], -1, 0
	s_and_b64 s[64:65], s[64:65], exec
	s_cselect_b32 s63, s94, s63
	s_cselect_b32 s64, s95, s66
	s_cselect_b32 s53, 0, s53
	s_and_b64 s[8:9], s[8:9], exec
	s_cselect_b32 s58, s64, s58
	s_cselect_b32 s4, s63, s4
	s_cselect_b32 s56, s53, s56
	s_cselect_b32 s53, 0, s21
	s_add_i32 s8, s23, 1
	s_cmp_lg_u32 s23, 2
	s_cselect_b32 s23, s8, 0
	s_waitcnt vmcnt(5)
	s_branch .Lg_bar

; DI void run_jobs(const Params& P, int rb, int jj_lo, int jj_hi, unsigned char* smem) {
;     ...
;         if (j == 2) {
;             const int r16 = lane & 15, q4 = lane >> 4;
;             const bf16_t* arow = xbr + (size_t)(wid * 16 + r16) * D + 8 * q4;
;             const bf16_t* wrow = Bt + ((size_t)(14 * 16) * 256 + r16) * 64 + 8 * q4;
;             f32x4 c = {0.f, 0.f, 0.f, 0.f};
; #pragma unroll 8
;             for (int kk = 0; kk < 32; ++kk) {
;                 const bf16x8 af = *(const bf16x8*)(arow + 32 * kk);
;                 const bf16x8 wf = *(const bf16x8*)(wrow + (size_t)(kk >> 1) * 16384 + (kk & 1) * 32);
;                 c = __builtin_amdgcn_mfma_f32_16x16x32_bf16(wf, af, c, 0, 0, 0);
;             }
;             if (q4 < 2) *(f32x4*)(ab + (size_t)(wid * 16 + r16) * 8 + q4 * 4) = c;
.LBB0_237:
	v_readlane_b32 s72, v248, 32
	s_mov_b32 s81, 0x2c000
	s_cmp_eq_u32 s15, 2
	v_readlane_b32 s73, v248, 33
	s_movk_i32 s77, 0x2000
	s_cbranch_scc0 .LBB0_246
	v_lshl_or_b32 v4, v178, 4, v180
	v_ashrrev_i32_e32 v5, 31, v4
	v_readlane_b32 s0, v247, 0
	v_lshlrev_b64 v[0:1], 11, v[4:5]
	v_readlane_b32 s1, v247, 1
	v_lshlrev_b32_e32 v2, 6, v180
	v_mov_b32_e32 v3, v177
	v_lshl_add_u64 v[8:9], s[0:1], 0, v[0:1]
	v_lshl_add_u64 v[6:7], s[94:95], 0, v[2:3]
	v_lshl_add_u64 v[8:9], v[8:9], 0, v[176:177]
	v_lshl_add_u64 v[6:7], v[6:7], 0, v[176:177]
	s_mov_b64 s[0:1], 0x700000
	s_mov_b64 s[6:7], 0x400
	v_lshl_add_u64 v[6:7], v[6:7], 0, s[0:1]
	s_mov_b64 s[0:1], 0x4000
	v_mov_b32_e32 v0, 0
	v_mov_b32_e32 v1, v0
	v_mov_b32_e32 v2, v0
	v_mov_b32_e32 v3, v0
	s_mov_b32 s4, 2
.Lnp_loop:
	global_load_dwordx4 v[10:13], v[8:9], off offset:-256
	global_load_dwordx4 v[14:17], v[8:9], off offset:-192
	global_load_dwordx4 v[18:21], v[8:9], off offset:-128
	global_load_dwordx4 v[22:25], v[8:9], off offset:-64
	global_load_dwordx4 v[26:29], v[8:9], off offset:0
	global_load_dwordx4 v[30:33], v[8:9], off offset:64
	global_load_dwordx4 v[34:37], v[8:9], off offset:128
	global_load_dwordx4 v[38:41], v[8:9], off offset:192
	global_load_dwordx4 v[42:45], v[8:9], off offset:256
	global_load_dwordx4 v[46:49], v[8:9], off offset:320
	global_load_dwordx4 v[50:53], v[8:9], off offset:384
	global_load_dwordx4 v[54:57], v[8:9], off offset:448
	global_load_dwordx4 v[58:61], v[8:9], off offset:512
	global_load_dwordx4 v[62:65], v[8:9], off offset:576
	global_load_dwordx4 v[66:69], v[8:9], off offset:640
	global_load_dwordx4 v[70:73], v[8:9], off offset:704
	global_load_dwordx4 v[74:77], v[6:7], off
	v_lshl_add_u64 v[138:139], v[6:7], 0, s[0:1]
	global_load_dwordx4 v[78:81], v[138:139], off
	v_lshl_add_u64 v[6:7], v[138:139], 0, s[0:1]
	global_load_dwordx4 v[82:85], v[6:7], off
	v_lshl_add_u64 v[138:139], v[6:7], 0, s[0:1]
	global_load_dwordx4 v[86:89], v[138:139], off
	v_lshl_add_u64 v[6:7], v[138:139], 0, s[0:1]
	global_load_dwordx4 v[90:93], v[6:7], off
	v_lshl_add_u64 v[138:139], v[6:7], 0, s[0:1]
	global_load_dwordx4 v[94:97], v[138:139], off
	v_lshl_add_u64 v[6:7], v[138:139], 0, s[0:1]
	global_load_dwordx4 v[98:101], v[6:7], off
	v_lshl_add_u64 v[138:139], v[6:7], 0, s[0:1]
	global_load_dwordx4 v[102:105], v[138:139], off
	v_lshl_add_u64 v[6:7], v[138:139], 0, s[0:1]
	global_load_dwordx4 v[106:109], v[6:7], off
	v_lshl_add_u64 v[138:139], v[6:7], 0, s[0:1]
	global_load_dwordx4 v[110:113], v[138:139], off
	v_lshl_add_u64 v[6:7], v[138:139], 0, s[0:1]
	global_load_dwordx4 v[114:117], v[6:7], off
	v_lshl_add_u64 v[138:139], v[6:7], 0, s[0:1]
	global_load_dwordx4 v[118:121], v[138:139], off
	v_lshl_add_u64 v[6:7], v[138:139], 0, s[0:1]
	global_load_dwordx4 v[122:125], v[6:7], off
	v_lshl_add_u64 v[138:139], v[6:7], 0, s[0:1]
	global_load_dwordx4 v[126:129], v[138:139], off
	v_lshl_add_u64 v[6:7], v[138:139], 0, s[0:1]
	global_load_dwordx4 v[130:133], v[6:7], off
	v_lshl_add_u64 v[138:139], v[6:7], 0, s[0:1]
	global_load_dwordx4 v[134:137], v[138:139], off
	v_lshl_add_u64 v[6:7], v[138:139], 0, s[0:1]
	v_lshl_add_u64 v[8:9], v[8:9], 0, s[6:7]
	s_add_i32 s4, s4, -1
	s_waitcnt vmcnt(15)
	v_mfma_f32_16x16x32_bf16 v[0:3], v[74:77], v[10:13], v[0:3]
	s_waitcnt vmcnt(14)
	v_mfma_f32_16x16x32_bf16 v[0:3], v[78:81], v[14:17], v[0:3]
	s_waitcnt vmcnt(13)
	v_mfma_f32_16x16x32_bf16 v[0:3], v[82:85], v[18:21], v[0:3]
	s_waitcnt vmcnt(12)
	v_mfma_f32_16x16x32_bf16 v[0:3], v[86:89], v[22:25], v[0:3]
	s_waitcnt vmcnt(11)
	v_mfma_f32_16x16x32_bf16 v[0:3], v[90:93], v[26:29], v[0:3]
	s_waitcnt vmcnt(10)
	v_mfma_f32_16x16x32_bf16 v[0:3], v[94:97], v[30:33], v[0:3]
	s_waitcnt vmcnt(9)
	v_mfma_f32_16x16x32_bf16 v[0:3], v[98:101], v[34:37], v[0:3]
	s_waitcnt vmcnt(8)
	v_mfma_f32_16x16x32_bf16 v[0:3], v[102:105], v[38:41], v[0:3]
	s_waitcnt vmcnt(7)
	v_mfma_f32_16x16x32_bf16 v[0:3], v[106:109], v[42:45], v[0:3]
	s_waitcnt vmcnt(6)
	v_mfma_f32_16x16x32_bf16 v[0:3], v[110:113], v[46:49], v[0:3]
	s_waitcnt vmcnt(5)
	v_mfma_f32_16x16x32_bf16 v[0:3], v[114:117], v[50:53], v[0:3]
	s_waitcnt vmcnt(4)
	v_mfma_f32_16x16x32_bf16 v[0:3], v[118:121], v[54:57], v[0:3]
	s_waitcnt vmcnt(3)
	v_mfma_f32_16x16x32_bf16 v[0:3], v[122:125], v[58:61], v[0:3]
	s_waitcnt vmcnt(2)
	v_mfma_f32_16x16x32_bf16 v[0:3], v[126:129], v[62:65], v[0:3]
	s_waitcnt vmcnt(1)
	v_mfma_f32_16x16x32_bf16 v[0:3], v[130:133], v[66:69], v[0:3]
	s_waitcnt vmcnt(0)
	v_mfma_f32_16x16x32_bf16 v[0:3], v[134:137], v[70:73], v[0:3]
	s_cmp_eq_u32 s4, 0
	s_cbranch_scc0 .Lnp_loop
	v_cmp_gt_u32_e32 vcc, 32, v245
	s_and_saveexec_b64 s[6:7], vcc
	s_cbranch_execz .LBB0_242
	v_readlane_b32 s0, v248, 48
	v_lshlrev_b64 v[4:5], 5, v[4:5]
	v_readlane_b32 s1, v248, 49
	v_lshlrev_b32_e32 v176, 2, v183
	s_nop 0
	v_lshl_add_u64 v[4:5], s[0:1], 0, v[4:5]
	v_lshl_add_u64 v[4:5], v[4:5], 0, v[176:177]
	global_store_dwordx4 v[4:5], v[0:3], off

; DI unsigned pk_bf16(float a, float b) { bf2_t v = __builtin_convertvector((f2_t){a, b}, bf2_t); return __builtin_bit_cast(unsigned, v); }
; DI int tid_() { int t = threadIdx.x; asm volatile("" : "+v"(t)); return t; }
; DI void transpose_tile(const float* __restrict__ src, int Nsrc, int K, bf16_t* __restrict__ dst, int mode, int k0, int n0, float* tile  ) {
;     const int tid = tid_();
;     const int n4 = (tid & 15) * 4;
;     const int c = colmap(mode, n0 + n4);
; #pragma unroll
;     for (int i = 0; i < 2; ++i) {
;         const int kk = (tid >> 4) + 32 * i;
;         f32x4 v = {0.f, 0.f, 0.f, 0.f};
;         if (c >= 0) v = *(const f32x4*)(src + (size_t)(k0 + kk) * Nsrc + c);
;         tile[kk * 65 + n4] = v[0]; tile[kk * 65 + n4 + 1] = v[1]; tile[kk * 65 + n4 + 2] = v[2]; tile[kk * 65 + n4 + 3] = v[3];
;     }
;     __syncthreads();
;     const int n = tid >> 3, ks = (tid & 7) * 8;
;     u32x4 w;
;     w.x = pk_bf16(tile[(ks + 0) * 65 + n], tile[(ks + 1) * 65 + n]);
;     w.y = pk_bf16(tile[(ks + 2) * 65 + n], tile[(ks + 3) * 65 + n]);
;     w.z = pk_bf16(tile[(ks + 4) * 65 + n], tile[(ks + 5) * 65 + n]);
;     w.w = pk_bf16(tile[(ks + 6) * 65 + n], tile[(ks + 7) * 65 + n]);
;     *(u32x4*)(dst + ((size_t)((n0 >> 8) * (K >> 6) + (k0 >> 6)) * 256 + (n0 & 255) + n) * 64 + ks) = w;
;     __syncthreads();
; DI void prep_weights(const Params& P, unsigned char* smem, int L, int vb, int nvb, int part  ) {
;     ...
;         else if (idx < E5) { const int t = idx - E4; const int kt = t / 16, nt = t % 16;
;             transpose_tile(P.ple_w_gate + (size_t)L * D * D, D, D, (bf16_t*)(ws + OFF_WG + L * SZ_WSQ), 0, kt * 64, nt * 64, tile); }
;         else { const int t = idx - E5; const int kt = t / 16, nt = t % 16;
;             transpose_tile(P.ple_w_proj + (size_t)L * PLE * D, D, PLE, (bf16_t*)(ws + OFF_WP + L * SZ_WP), 0, kt * 64, nt * 64, tile); }
.LBB0_333:
	s_add_i32 s11, s10, 0xffffef80
	s_cmpk_gt_i32 s10, 0x57f
	s_cselect_b64 s[6:7], -1, 0
	s_add_i32 s4, s10, 0xfffff240
	s_cmp_lt_u32 s4, 0xfffffd40
	s_cselect_b64 s[12:13], -1, 0
	s_and_b64 s[6:7], s[6:7], s[12:13]
	s_cmpk_gt_u32 s11, 0x3bf
	s_cselect_b64 s[12:13], -1, 0
	s_and_b64 s[6:7], s[6:7], s[12:13]
	s_andn2_b64 vcc, exec, s[6:7]
	s_cbranch_vccnz .LBB0_332
	s_cmpk_gt_u32 s10, 0xaff
	s_mov_b64 s[6:7], -1
	s_cbranch_scc0 .LBB0_362
	s_cmpk_gt_u32 s10, 0x107f
	s_cbranch_scc0 .LBB0_359
	s_cmpk_gt_u32 s10, 0x143f
	s_cbranch_scc0 .LBB0_346
	s_cmpk_gt_u32 s10, 0x153f
	s_cbranch_scc0 .LBB0_343
	s_and_b32 s12, s9, 0x3c0
	s_cmpk_gt_u32 s10, 0x163f
	s_cbranch_scc0 .LBB0_340
	v_mov_b32_e32 v8, v223
	s_and_b32 s4, s8, 0x7fffffc0
	s_addk_i32 s4, 0xa700
	v_lshlrev_b32_e32 v0, 2, v8
	v_and_b32_e32 v0, 60, v0
	v_ashrrev_i32_e32 v9, 4, v8
	v_or_b32_e32 v1, s12, v0
	v_readlane_b32 s16, v250, 58
	v_add_u32_e32 v6, s4, v9
	v_lshlrev_b32_e32 v176, 2, v1
	v_readlane_b32 s26, v249, 4
	v_readlane_b32 s27, v249, 5
	v_ashrrev_i32_e32 v7, 31, v6
	v_lshlrev_b32_e32 v10, 2, v0
	v_lshl_add_u64 v[4:5], s[26:27], 0, v[176:177]
	v_lshlrev_b64 v[0:1], 12, v[6:7]
	v_lshl_add_u64 v[0:1], v[4:5], 0, v[0:1]
	global_load_dwordx4 v[0:3], v[0:1], off
	s_movk_i32 s0, 0x104
	v_mul_lo_u32 v7, v9, s0
	v_add3_u32 v7, 0, v10, v7
	s_and_b32 s6, s10, 12
	s_lshr_b32 s4, s4, 6
	s_add_i32 s4, s4, s6
	s_lshl_b64 s[6:7], s[4:5], 8
	s_and_b32 s4, s9, 0xc0
	s_or_b32 s6, s6, s4
	v_readlane_b32 s17, v250, 59
	v_readlane_b32 s18, v250, 60
	v_readlane_b32 s19, v250, 61
	v_readlane_b32 s20, v250, 62
	v_readlane_b32 s21, v250, 63
	v_readlane_b32 s22, v249, 0
	v_readlane_b32 s23, v249, 1
	v_readlane_b32 s24, v249, 2
	v_readlane_b32 s25, v249, 3
	v_readlane_b32 s28, v249, 6
	v_readlane_b32 s29, v249, 7
	v_readlane_b32 s30, v249, 8
	v_readlane_b32 s31, v249, 9
	s_waitcnt vmcnt(0)
	ds_write2_b32 v7, v0, v1 offset1:1
	ds_write2_b32 v7, v2, v3 offset0:2 offset1:3
	v_add_u32_e32 v0, 32, v6
	v_ashrrev_i32_e32 v1, 31, v0
	v_lshlrev_b64 v[0:1], 12, v[0:1]
	v_lshl_add_u64 v[0:1], v[4:5], 0, v[0:1]
	global_load_dwordx4 v[0:3], v[0:1], off
	v_add_u32_e32 v4, 0x2080, v7
	s_waitcnt vmcnt(0)
	ds_write2_b32 v4, v0, v1 offset1:1
	v_add_u32_e32 v0, 0x2088, v7
	ds_write2_b32 v0, v2, v3 offset1:1
	v_lshlrev_b32_e32 v0, 3, v8
	v_ashrrev_i32_e32 v4, 3, v8
	v_and_b32_e32 v8, 56, v0
	v_mul_u32_u24_e32 v0, 0x104, v8
	v_lshlrev_b32_e32 v1, 2, v4
	v_add3_u32 v5, 0, v0, v1
	s_waitcnt lgkmcnt(0)
	s_barrier
	ds_read2_b32 v[0:1], v5 offset1:65
	ds_read2_b32 v[2:3], v5 offset0:130 offset1:195
	v_add_u32_e32 v5, 0x400, v5
	ds_read2_b32 v[6:7], v5 offset0:134 offset1:199
	v_lshlrev_b32_e32 v176, 1, v8
	v_and_b32_e32 v245, 64, v176
	v_and_b32_e32 v176, 48, v176
	v_lshl_or_b32 v176, v245, 8, v176
	s_waitcnt lgkmcnt(2)
	v_cvt_pk_bf16_f32 v0, v0, v1
	s_waitcnt lgkmcnt(1)
	v_cvt_pk_bf16_f32 v1, v2, v3
	ds_read2_b32 v[2:3], v5 offset0:4 offset1:69
	v_ashrrev_i32_e32 v5, 31, v4
	v_lshl_add_u64 v[4:5], s[6:7], 0, v[4:5]
	v_readlane_b32 s6, v250, 14
	v_and_b32_e32 v246, 0xff, v4
	v_lshlrev_b32_e32 v246, 6, v246
	v_and_b32_e32 v4, 0xffffff00, v4
	v_lshlrev_b64 v[4:5], 7, v[4:5]
	v_or_b32_e32 v4, v4, v246
	v_readlane_b32 s7, v250, 15
	s_waitcnt lgkmcnt(0)
	v_cvt_pk_bf16_f32 v2, v2, v3
	v_cvt_pk_bf16_f32 v3, v6, v7
	v_lshl_add_u64 v[4:5], s[6:7], 0, v[4:5]
	v_lshl_add_u64 v[4:5], v[4:5], 0, v[176:177]
	global_store_dwordx4 v[4:5], v[0:3], off
	s_barrier
	s_mov_b64 s[6:7], 0
.LBB0_340:
	s_andn2_b64 vcc, exec, s[6:7]
	s_cbranch_vccnz .LBB0_342
	v_mov_b32_e32 v8, v223
	s_and_b32 s4, s8, 0x7fc0
	s_addk_i32 s4, 0xab00
	v_lshlrev_b32_e32 v0, 2, v8
	v_and_b32_e32 v0, 60, v0
	v_ashrrev_i32_e32 v9, 4, v8
	v_or_b32_e32 v1, s12, v0
	v_readlane_b32 s12, v250, 58
	v_add_u32_e32 v6, s4, v9
	v_lshlrev_b32_e32 v176, 2, v1
	v_readlane_b32 s24, v249, 6
	v_readlane_b32 s25, v249, 7
	v_ashrrev_i32_e32 v7, 31, v6
	v_lshlrev_b32_e32 v10, 2, v0
	v_lshl_add_u64 v[4:5], s[24:25], 0, v[176:177]
	v_lshlrev_b64 v[0:1], 12, v[6:7]
	v_lshl_add_u64 v[0:1], v[4:5], 0, v[0:1]
	global_load_dwordx4 v[0:3], v[0:1], off
	s_movk_i32 s0, 0x104
	v_mul_lo_u32 v7, v9, s0
	v_add3_u32 v7, 0, v10, v7
	s_and_b32 s6, s8, 48
	s_lshr_b32 s4, s4, 6
	s_add_i32 s4, s4, s6
	s_lshl_b64 s[6:7], s[4:5], 8
	s_and_b32 s4, s9, 0xc0
	s_or_b32 s6, s6, s4
	v_readlane_b32 s13, v250, 59
	v_readlane_b32 s14, v250, 60
	v_readlane_b32 s15, v250, 61
	v_readlane_b32 s16, v250, 62
	v_readlane_b32 s17, v250, 63
	v_readlane_b32 s18, v249, 0
	v_readlane_b32 s19, v249, 1
	v_readlane_b32 s20, v249, 2
	v_readlane_b32 s21, v249, 3
	v_readlane_b32 s22, v249, 4
	v_readlane_b32 s23, v249, 5
	v_readlane_b32 s26, v249, 8
	v_readlane_b32 s27, v249, 9
	s_waitcnt vmcnt(0)
	ds_write2_b32 v7, v0, v1 offset1:1
	ds_write2_b32 v7, v2, v3 offset0:2 offset1:3
	v_add_u32_e32 v0, 32, v6
	v_ashrrev_i32_e32 v1, 31, v0
	v_lshlrev_b64 v[0:1], 12, v[0:1]
	v_lshl_add_u64 v[0:1], v[4:5], 0, v[0:1]
	global_load_dwordx4 v[0:3], v[0:1], off
	v_add_u32_e32 v4, 0x2080, v7
	s_waitcnt vmcnt(0)
	ds_write2_b32 v4, v0, v1 offset1:1
	v_add_u32_e32 v0, 0x2088, v7
	ds_write2_b32 v0, v2, v3 offset1:1
	v_lshlrev_b32_e32 v0, 3, v8
	v_ashrrev_i32_e32 v4, 3, v8
	v_and_b32_e32 v8, 56, v0
	v_mul_u32_u24_e32 v0, 0x104, v8
	v_lshlrev_b32_e32 v1, 2, v4
	v_add3_u32 v5, 0, v0, v1
	s_waitcnt lgkmcnt(0)
	s_barrier
	ds_read2_b32 v[0:1], v5 offset1:65
	ds_read2_b32 v[2:3], v5 offset0:130 offset1:195
	v_add_u32_e32 v5, 0x400, v5
	ds_read2_b32 v[6:7], v5 offset0:134 offset1:199
	v_lshlrev_b32_e32 v176, 1, v8
	v_and_b32_e32 v245, 64, v176
	v_and_b32_e32 v176, 48, v176
	v_lshl_or_b32 v176, v245, 8, v176
	s_waitcnt lgkmcnt(2)
	v_cvt_pk_bf16_f32 v0, v0, v1
	s_waitcnt lgkmcnt(1)
	v_cvt_pk_bf16_f32 v1, v2, v3
	ds_read2_b32 v[2:3], v5 offset0:4 offset1:69
	v_ashrrev_i32_e32 v5, 31, v4
	v_lshl_add_u64 v[4:5], s[6:7], 0, v[4:5]
	v_readlane_b32 s6, v250, 12
	v_and_b32_e32 v246, 0xff, v4
	v_lshlrev_b32_e32 v246, 6, v246
	v_and_b32_e32 v4, 0xffffff00, v4
	v_lshlrev_b64 v[4:5], 7, v[4:5]
	v_or_b32_e32 v4, v4, v246
	v_readlane_b32 s7, v250, 13
	s_waitcnt lgkmcnt(0)
	v_cvt_pk_bf16_f32 v2, v2, v3
	v_cvt_pk_bf16_f32 v3, v6, v7
	v_lshl_add_u64 v[4:5], s[6:7], 0, v[4:5]
	v_lshl_add_u64 v[4:5], v[4:5], 0, v[176:177]
	global_store_dwordx4 v[4:5], v[0:3], off
	s_barrier

; DI unsigned pk_bf16(float a, float b) { bf2_t v = __builtin_convertvector((f2_t){a, b}, bf2_t); return __builtin_bit_cast(unsigned, v); }
; DI int tid_() { int t = threadIdx.x; asm volatile("" : "+v"(t)); return t; }
; DI void transpose_tile(const float* __restrict__ src, int Nsrc, int K, bf16_t* __restrict__ dst, int mode, int k0, int n0, float* tile  ) {
;     const int tid = tid_();
;     const int n4 = (tid & 15) * 4;
;     const int c = colmap(mode, n0 + n4);
; #pragma unroll
;     for (int i = 0; i < 2; ++i) {
;         const int kk = (tid >> 4) + 32 * i;
;         f32x4 v = {0.f, 0.f, 0.f, 0.f};
;         if (c >= 0) v = *(const f32x4*)(src + (size_t)(k0 + kk) * Nsrc + c);
;         tile[kk * 65 + n4] = v[0]; tile[kk * 65 + n4 + 1] = v[1]; tile[kk * 65 + n4 + 2] = v[2]; tile[kk * 65 + n4 + 3] = v[3];
;     }
;     __syncthreads();
;     const int n = tid >> 3, ks = (tid & 7) * 8;
;     u32x4 w;
;     w.x = pk_bf16(tile[(ks + 0) * 65 + n], tile[(ks + 1) * 65 + n]);
;     w.y = pk_bf16(tile[(ks + 2) * 65 + n], tile[(ks + 3) * 65 + n]);
;     w.z = pk_bf16(tile[(ks + 4) * 65 + n], tile[(ks + 5) * 65 + n]);
;     w.w = pk_bf16(tile[(ks + 6) * 65 + n], tile[(ks + 7) * 65 + n]);
;     *(u32x4*)(dst + ((size_t)((n0 >> 8) * (K >> 6) + (k0 >> 6)) * 256 + (n0 & 255) + n) * 64 + ks) = w;
;     __syncthreads();
; DI void prep_weights(const Params& P, unsigned char* smem, int L, int vb, int nvb, int part  ) {
;     ...
;         else if (idx < E4) { const int t = idx - E3; const int kt = t / 16, nt = t % 16;
;             transpose_tile(P.mix_w_out + (size_t)L * D * D, D, D, (bf16_t*)(ws + OFF_WOUT + L * SZ_WSQ), 0, kt * 64, nt * 64, tile); }
.LBB0_343:
	s_andn2_b64 vcc, exec, s[6:7]
	s_cbranch_vccnz .LBB0_345
	v_mov_b32_e32 v8, v223
	s_and_b32 s4, s8, 0x7fc0
	s_addk_i32 s4, 0xaf00
	v_lshlrev_b32_e32 v0, 2, v8
	s_and_b32 s6, s9, 0x3c0
	v_and_b32_e32 v0, 60, v0
	v_ashrrev_i32_e32 v9, 4, v8
	v_or_b32_e32 v1, s6, v0
	v_readlane_b32 s12, v250, 58
	v_add_u32_e32 v6, s4, v9
	v_lshlrev_b32_e32 v176, 2, v1
	v_readlane_b32 s20, v249, 2
	v_readlane_b32 s21, v249, 3
	v_ashrrev_i32_e32 v7, 31, v6
	v_lshlrev_b32_e32 v10, 2, v0
	v_lshl_add_u64 v[4:5], s[20:21], 0, v[176:177]
	v_lshlrev_b64 v[0:1], 12, v[6:7]
	v_lshl_add_u64 v[0:1], v[4:5], 0, v[0:1]
	global_load_dwordx4 v[0:3], v[0:1], off
	s_movk_i32 s0, 0x104
	v_mul_lo_u32 v7, v9, s0
	v_add3_u32 v7, 0, v10, v7
	s_and_b32 s6, s8, 48
	s_lshr_b32 s4, s4, 6
	s_add_i32 s4, s4, s6
	s_lshl_b64 s[6:7], s[4:5], 8
	s_and_b32 s4, s9, 0xc0
	s_or_b32 s6, s6, s4
	v_readlane_b32 s13, v250, 59
	v_readlane_b32 s14, v250, 60
	v_readlane_b32 s15, v250, 61
	v_readlane_b32 s16, v250, 62
	v_readlane_b32 s17, v250, 63
	v_readlane_b32 s18, v249, 0
	v_readlane_b32 s19, v249, 1
	v_readlane_b32 s22, v249, 4
	v_readlane_b32 s23, v249, 5
	v_readlane_b32 s24, v249, 6
	v_readlane_b32 s25, v249, 7
	v_readlane_b32 s26, v249, 8
	v_readlane_b32 s27, v249, 9
	s_waitcnt vmcnt(0)
	ds_write2_b32 v7, v0, v1 offset1:1
	ds_write2_b32 v7, v2, v3 offset0:2 offset1:3
	v_add_u32_e32 v0, 32, v6
	v_ashrrev_i32_e32 v1, 31, v0
	v_lshlrev_b64 v[0:1], 12, v[0:1]
	v_lshl_add_u64 v[0:1], v[4:5], 0, v[0:1]
	global_load_dwordx4 v[0:3], v[0:1], off
	v_add_u32_e32 v4, 0x2080, v7
	s_waitcnt vmcnt(0)
	ds_write2_b32 v4, v0, v1 offset1:1
	v_add_u32_e32 v0, 0x2088, v7
	ds_write2_b32 v0, v2, v3 offset1:1
	v_lshlrev_b32_e32 v0, 3, v8
	v_ashrrev_i32_e32 v4, 3, v8
	v_and_b32_e32 v8, 56, v0
	v_mul_u32_u24_e32 v0, 0x104, v8
	v_lshlrev_b32_e32 v1, 2, v4
	v_add3_u32 v5, 0, v0, v1
	s_waitcnt lgkmcnt(0)
	s_barrier
	ds_read2_b32 v[0:1], v5 offset1:65
	ds_read2_b32 v[2:3], v5 offset0:130 offset1:195
	v_add_u32_e32 v5, 0x400, v5
	ds_read2_b32 v[6:7], v5 offset0:134 offset1:199
	v_lshlrev_b32_e32 v176, 1, v8
	v_and_b32_e32 v245, 64, v176
	v_and_b32_e32 v176, 48, v176
	v_lshl_or_b32 v176, v245, 8, v176
	s_waitcnt lgkmcnt(2)
	v_cvt_pk_bf16_f32 v0, v0, v1
	s_waitcnt lgkmcnt(1)
	v_cvt_pk_bf16_f32 v1, v2, v3
	ds_read2_b32 v[2:3], v5 offset0:4 offset1:69
	v_ashrrev_i32_e32 v5, 31, v4
	v_lshl_add_u64 v[4:5], s[6:7], 0, v[4:5]
	v_readlane_b32 s6, v250, 16
	v_and_b32_e32 v246, 0xff, v4
	v_lshlrev_b32_e32 v246, 6, v246
	v_and_b32_e32 v4, 0xffffff00, v4
	v_lshlrev_b64 v[4:5], 7, v[4:5]
	v_or_b32_e32 v4, v4, v246
	v_readlane_b32 s7, v250, 17
	s_waitcnt lgkmcnt(0)
	v_cvt_pk_bf16_f32 v2, v2, v3
	v_cvt_pk_bf16_f32 v3, v6, v7
	v_lshl_add_u64 v[4:5], s[6:7], 0, v[4:5]
	v_lshl_add_u64 v[4:5], v[4:5], 0, v[176:177]
	global_store_dwordx4 v[4:5], v[0:3], off
	s_barrier

; DI unsigned pk_bf16(float a, float b) { bf2_t v = __builtin_convertvector((f2_t){a, b}, bf2_t); return __builtin_bit_cast(unsigned, v); }
; DI void transpose_tile(const float* __restrict__ src, int Nsrc, int K, bf16_t* __restrict__ dst, int mode, int k0, int n0, float* tile  ) {
;     ...
;     __syncthreads();
;     const int n = tid >> 3, ks = (tid & 7) * 8;
;     u32x4 w;
;     w.x = pk_bf16(tile[(ks + 0) * 65 + n], tile[(ks + 1) * 65 + n]);
;     w.y = pk_bf16(tile[(ks + 2) * 65 + n], tile[(ks + 3) * 65 + n]);
;     w.z = pk_bf16(tile[(ks + 4) * 65 + n], tile[(ks + 5) * 65 + n]);
;     w.w = pk_bf16(tile[(ks + 6) * 65 + n], tile[(ks + 7) * 65 + n]);
;     *(u32x4*)(dst + ((size_t)((n0 >> 8) * (K >> 6) + (k0 >> 6)) * 256 + (n0 & 255) + n) * 64 + ks) = w;
;     __syncthreads();
.LBB0_357:
	s_or_b64 exec, exec, s[6:7]
	v_add_u32_e32 v4, 0x2080, v10
	s_waitcnt vmcnt(0)
	ds_write2_b32 v4, v0, v1 offset1:1
	v_add_u32_e32 v0, 0x2088, v10
	ds_write2_b32 v0, v2, v3 offset1:1
	v_lshlrev_b32_e32 v0, 3, v8
	v_ashrrev_i32_e32 v4, 3, v8
	v_and_b32_e32 v8, 56, v0
	v_mul_u32_u24_e32 v0, 0x104, v8
	v_lshlrev_b32_e32 v1, 2, v4
	v_add3_u32 v5, 0, v0, v1
	s_waitcnt lgkmcnt(0)
	s_barrier
	ds_read2_b32 v[0:1], v5 offset1:65
	ds_read2_b32 v[2:3], v5 offset0:130 offset1:195
	s_lshr_b32 s6, s4, 4
	s_and_b32 s6, s6, 0xf0
	v_add_u32_e32 v5, 0x400, v5
	s_add_i32 s6, s6, s11
	s_waitcnt lgkmcnt(1)
	v_cvt_pk_bf16_f32 v0, v0, v1
	s_waitcnt lgkmcnt(0)
	v_cvt_pk_bf16_f32 v1, v2, v3
	ds_read2_b32 v[2:3], v5 offset0:4 offset1:69
	ds_read2_b32 v[6:7], v5 offset0:134 offset1:199
	s_lshl_b32 s6, s6, 8
	s_and_b32 s4, s4, 0xc0
	s_or_b32 s4, s6, s4
	v_ashrrev_i32_e32 v5, 31, v4
	v_lshl_add_u64 v[4:5], v[4:5], 0, s[4:5]
	v_readlane_b32 s6, v250, 18
	v_and_b32_e32 v246, 0xff, v4
	v_lshlrev_b32_e32 v246, 6, v246
	v_and_b32_e32 v4, 0xffffff00, v4
	v_lshlrev_b64 v[4:5], 7, v[4:5]
	v_or_b32_e32 v4, v4, v246
	v_readlane_b32 s7, v250, 19
	v_lshlrev_b32_e32 v176, 1, v8
	v_and_b32_e32 v245, 64, v176
	v_and_b32_e32 v176, 48, v176
	v_lshl_or_b32 v176, v245, 8, v176
	s_waitcnt lgkmcnt(1)
	v_cvt_pk_bf16_f32 v2, v2, v3
	v_lshl_add_u64 v[4:5], s[6:7], 0, v[4:5]
	s_waitcnt lgkmcnt(0)
	v_cvt_pk_bf16_f32 v3, v6, v7
	v_lshl_add_u64 v[4:5], v[4:5], 0, v[176:177]
	global_store_dwordx4 v[4:5], v[0:3], off
	s_barrier

; DI unsigned pk_bf16(float a, float b) { bf2_t v = __builtin_convertvector((f2_t){a, b}, bf2_t); return __builtin_bit_cast(unsigned, v); }
; DI int tid_() { int t = threadIdx.x; asm volatile("" : "+v"(t)); return t; }
; DI void transpose_tile(const float* __restrict__ src, int Nsrc, int K, bf16_t* __restrict__ dst, int mode, int k0, int n0, float* tile  ) {
;     const int tid = tid_();
;     const int n4 = (tid & 15) * 4;
;     const int c = colmap(mode, n0 + n4);
; #pragma unroll
;     for (int i = 0; i < 2; ++i) {
;         const int kk = (tid >> 4) + 32 * i;
;         f32x4 v = {0.f, 0.f, 0.f, 0.f};
;         if (c >= 0) v = *(const f32x4*)(src + (size_t)(k0 + kk) * Nsrc + c);
;         tile[kk * 65 + n4] = v[0]; tile[kk * 65 + n4 + 1] = v[1]; tile[kk * 65 + n4 + 2] = v[2]; tile[kk * 65 + n4 + 3] = v[3];
;     }
;     __syncthreads();
;     const int n = tid >> 3, ks = (tid & 7) * 8;
;     u32x4 w;
;     w.x = pk_bf16(tile[(ks + 0) * 65 + n], tile[(ks + 1) * 65 + n]);
;     w.y = pk_bf16(tile[(ks + 2) * 65 + n], tile[(ks + 3) * 65 + n]);
;     w.z = pk_bf16(tile[(ks + 4) * 65 + n], tile[(ks + 5) * 65 + n]);
;     w.w = pk_bf16(tile[(ks + 6) * 65 + n], tile[(ks + 7) * 65 + n]);
;     *(u32x4*)(dst + ((size_t)((n0 >> 8) * (K >> 6) + (k0 >> 6)) * 256 + (n0 & 255) + n) * 64 + ks) = w;
;     __syncthreads();
; DI void prep_weights(const Params& P, unsigned char* smem, int L, int vb, int nvb, int part  ) {
;     ...
;         else if (idx < E2) { const int q = idx - E1; const int j = L * 2 + q / T_W2, t = q % T_W2; const int kt = t / 16, nt = t % 16;
;             transpose_tile(P.ffn_w_out + (size_t)j * DFF * D, D, DFF, (bf16_t*)(ws + OFF_W2 + j * SZ_W2), 0, kt * 64, nt * 64, tile); }
.LBB0_359:
	s_andn2_b64 vcc, exec, s[6:7]
	s_cbranch_vccnz .LBB0_361
	v_mov_b32_e32 v8, v223
	s_add_i32 s4, s8, 0xffffc900
	s_add_i32 s7, s9, 0xfffc9000
	s_and_b32 s6, s4, 0xfc0
	v_lshlrev_b32_e32 v0, 2, v8
	s_and_b32 s11, s7, 0x3c0
	v_and_b32_e32 v0, 60, v0
	v_ashrrev_i32_e32 v9, 4, v8
	v_or_b32_e32 v1, s11, v0
	v_readlane_b32 s12, v250, 42
	v_add_u32_e32 v6, s6, v9
	v_lshlrev_b32_e32 v176, 2, v1
	v_readlane_b32 s13, v250, 43
	v_ashrrev_i32_e32 v7, 31, v6
	v_lshlrev_b32_e32 v10, 2, v0
	v_lshl_add_u64 v[4:5], s[12:13], 0, v[176:177]
	v_lshlrev_b64 v[0:1], 12, v[6:7]
	v_lshl_add_u64 v[0:1], v[4:5], 0, v[0:1]
	global_load_dwordx4 v[0:3], v[0:1], off
	s_movk_i32 s0, 0x104
	v_mul_lo_u32 v7, v9, s0
	v_add3_u32 v7, 0, v10, v7
	s_bfe_u32 s6, s7, 0x20008
	s_mul_i32 s6, s6, 44
	s_bfe_u32 s4, s4, 0x60006
	s_add_i32 s6, s6, s4
	s_lshl_b32 s4, s6, 8
	s_and_b32 s6, s7, 0xc0
	s_or_b32 s4, s4, s6
	v_readlane_b32 s6, v250, 40
	v_readlane_b32 s7, v250, 41
	s_waitcnt vmcnt(0)
	ds_write2_b32 v7, v0, v1 offset1:1
	ds_write2_b32 v7, v2, v3 offset0:2 offset1:3
	v_add_u32_e32 v0, 32, v6
	v_ashrrev_i32_e32 v1, 31, v0
	v_lshlrev_b64 v[0:1], 12, v[0:1]
	v_lshl_add_u64 v[0:1], v[4:5], 0, v[0:1]
	global_load_dwordx4 v[0:3], v[0:1], off
	v_add_u32_e32 v4, 0x2080, v7
	s_waitcnt vmcnt(0)
	ds_write2_b32 v4, v0, v1 offset1:1
	v_add_u32_e32 v0, 0x2088, v7
	ds_write2_b32 v0, v2, v3 offset1:1
	v_lshlrev_b32_e32 v0, 3, v8
	v_ashrrev_i32_e32 v4, 3, v8
	v_and_b32_e32 v8, 56, v0
	v_mul_u32_u24_e32 v0, 0x104, v8
	v_lshlrev_b32_e32 v1, 2, v4
	v_add3_u32 v5, 0, v0, v1
	s_waitcnt lgkmcnt(0)
	s_barrier
	ds_read2_b32 v[0:1], v5 offset1:65
	ds_read2_b32 v[2:3], v5 offset0:130 offset1:195
	v_add_u32_e32 v5, 0x400, v5
	ds_read2_b32 v[6:7], v5 offset0:134 offset1:199
	v_lshlrev_b32_e32 v176, 1, v8
	v_and_b32_e32 v245, 64, v176
	v_and_b32_e32 v176, 48, v176
	v_lshl_or_b32 v176, v245, 8, v176
	s_waitcnt lgkmcnt(2)
	v_cvt_pk_bf16_f32 v0, v0, v1
	s_waitcnt lgkmcnt(1)
	v_cvt_pk_bf16_f32 v1, v2, v3
	ds_read2_b32 v[2:3], v5 offset0:4 offset1:69
	v_ashrrev_i32_e32 v5, 31, v4
	v_lshl_add_u64 v[4:5], v[4:5], 0, s[4:5]
	v_and_b32_e32 v246, 0xff, v4
	v_lshlrev_b32_e32 v246, 6, v246
	v_and_b32_e32 v4, 0xffffff00, v4
	v_lshlrev_b64 v[4:5], 7, v[4:5]
	v_or_b32_e32 v4, v4, v246
	v_lshl_add_u64 v[4:5], s[6:7], 0, v[4:5]
	s_waitcnt lgkmcnt(0)
	v_cvt_pk_bf16_f32 v2, v2, v3
	v_cvt_pk_bf16_f32 v3, v6, v7
	v_lshl_add_u64 v[4:5], v[4:5], 0, v[176:177]
	global_store_dwordx4 v[4:5], v[0:3], off
	s_barrier

; DI unsigned pk_bf16(float a, float b) { bf2_t v = __builtin_convertvector((f2_t){a, b}, bf2_t); return __builtin_bit_cast(unsigned, v); }
; DI int tid_() { int t = threadIdx.x; asm volatile("" : "+v"(t)); return t; }
; DI void transpose_tile(const float* __restrict__ src, int Nsrc, int K, bf16_t* __restrict__ dst, int mode, int k0, int n0, float* tile  ) {
;     const int tid = tid_();
;     const int n4 = (tid & 15) * 4;
;     const int c = colmap(mode, n0 + n4);
; #pragma unroll
;     for (int i = 0; i < 2; ++i) {
;         const int kk = (tid >> 4) + 32 * i;
;         f32x4 v = {0.f, 0.f, 0.f, 0.f};
;         if (c >= 0) v = *(const f32x4*)(src + (size_t)(k0 + kk) * Nsrc + c);
;         tile[kk * 65 + n4] = v[0]; tile[kk * 65 + n4 + 1] = v[1]; tile[kk * 65 + n4 + 2] = v[2]; tile[kk * 65 + n4 + 3] = v[3];
;     }
;     __syncthreads();
;     const int n = tid >> 3, ks = (tid & 7) * 8;
;     u32x4 w;
;     w.x = pk_bf16(tile[(ks + 0) * 65 + n], tile[(ks + 1) * 65 + n]);
;     w.y = pk_bf16(tile[(ks + 2) * 65 + n], tile[(ks + 3) * 65 + n]);
;     w.z = pk_bf16(tile[(ks + 4) * 65 + n], tile[(ks + 5) * 65 + n]);
;     w.w = pk_bf16(tile[(ks + 6) * 65 + n], tile[(ks + 7) * 65 + n]);
;     *(u32x4*)(dst + ((size_t)((n0 >> 8) * (K >> 6) + (k0 >> 6)) * 256 + (n0 & 255) + n) * 64 + ks) = w;
;     __syncthreads();
; DI void prep_weights(const Params& P, unsigned char* smem, int L, int vb, int nvb, int part  ) {
;     ...
;     for (int idx = vb; idx < E6; idx += nvb) {
;         const bool early = (idx < T_W1) || (idx >= E1 && idx < E1 + T_W2) || (idx >= E2 && idx < E3);
;         if (part != 2 && early != (part == 0)) continue;
;         if (idx < E1) { const int j = L * 2 + idx / T_W1, t = idx % T_W1; const int kt = t / 88, nt = t % 88;
;             transpose_tile(P.ffn_w_in + (size_t)j * D * 2 * DFF, 2 * DFF, D, (bf16_t*)(ws + OFF_W1 + j * SZ_W1), 1, kt * 64, nt * 64, tile); }
.LBB0_362:
	s_andn2_b64 vcc, exec, s[6:7]
	s_cbranch_vccnz .LBB0_331
	s_add_i32 s4, s10, 0xfa80
	s_and_b32 s6, s4, 0xffff
	s_mul_i32 s6, s6, 0xba2f
	s_lshr_b32 s11, s6, 22
	s_mul_i32 s6, s11, 0x58
	s_sub_i32 s4, s4, s6
	v_mov_b32_e32 v6, v223
	s_and_b32 s4, s4, 0xffff
	s_lshl_b32 s12, s4, 6
	v_lshlrev_b32_e32 v0, 2, v6
	v_and_b32_e32 v0, 60, v0
	v_or_b32_e32 v1, s12, v0
	v_bfe_i32 v2, v6, 2, 1
	s_lshl_b32 s6, s4, 5
	v_and_b32_e32 v2, 0xb00, v2
	v_lshlrev_b32_e32 v7, 2, v0
	v_lshrrev_b32_e32 v1, 3, v1
	s_and_b32 s6, s6, 0xfc0
	v_and_b32_e32 v0, 48, v7
	v_and_b32_e32 v1, 12, v1
	v_add_u32_e32 v2, s6, v2
	v_or3_b32 v0, v2, v0, v1
	v_readlane_b32 s6, v250, 44
	v_ashrrev_i32_e32 v8, 4, v6
	v_lshlrev_b32_e32 v176, 2, v0
	v_readlane_b32 s7, v250, 45
	v_lshl_add_u32 v9, s11, 6, v8
	s_movk_i32 s1, 0x5800
	v_lshl_add_u64 v[4:5], s[6:7], 0, v[176:177]
	v_mad_i64_i32 v[0:1], s[6:7], v9, s1, v[4:5]
	global_load_dwordx4 v[0:3], v[0:1], off
	s_movk_i32 s0, 0x104
	v_mul_lo_u32 v8, v8, s0
	v_add3_u32 v7, 0, v7, v8
	s_lshl_b32 s4, s4, 2
	s_and_b32 s4, s4, 0x1f0
	s_add_i32 s4, s4, s11
	s_lshl_b32 s4, s4, 8
	s_waitcnt vmcnt(0)
	ds_write2_b32 v7, v0, v1 offset1:1
	ds_write2_b32 v7, v2, v3 offset0:2 offset1:3
	v_add_u32_e32 v0, 32, v9
	v_mad_i64_i32 v[0:1], s[6:7], v0, s1, v[4:5]
	global_load_dwordx4 v[0:3], v[0:1], off
	v_add_u32_e32 v4, 0x2080, v7
	s_and_b32 s6, s12, 0xc0
	s_or_b32 s4, s4, s6
	v_readlane_b32 s6, v250, 38
	v_readlane_b32 s7, v250, 39
	s_waitcnt vmcnt(0)
	ds_write2_b32 v4, v0, v1 offset1:1
	v_add_u32_e32 v0, 0x2088, v7
	ds_write2_b32 v0, v2, v3 offset1:1
	v_lshlrev_b32_e32 v0, 3, v6
	v_ashrrev_i32_e32 v4, 3, v6
	v_and_b32_e32 v8, 56, v0
	v_mul_u32_u24_e32 v0, 0x104, v8
	v_lshlrev_b32_e32 v1, 2, v4
	v_add3_u32 v5, 0, v0, v1
	s_waitcnt lgkmcnt(0)
	s_barrier
	ds_read2_b32 v[0:1], v5 offset1:65
	ds_read2_b32 v[2:3], v5 offset0:130 offset1:195
	v_add_u32_e32 v5, 0x400, v5
	ds_read2_b32 v[6:7], v5 offset0:134 offset1:199
	v_lshlrev_b32_e32 v176, 1, v8
	v_and_b32_e32 v245, 64, v176
	v_and_b32_e32 v176, 48, v176
	v_lshl_or_b32 v176, v245, 8, v176
	s_waitcnt lgkmcnt(2)
	v_cvt_pk_bf16_f32 v0, v0, v1
	s_waitcnt lgkmcnt(1)
	v_cvt_pk_bf16_f32 v1, v2, v3
	ds_read2_b32 v[2:3], v5 offset0:4 offset1:69
	v_ashrrev_i32_e32 v5, 31, v4
	v_lshl_add_u64 v[4:5], v[4:5], 0, s[4:5]
	v_and_b32_e32 v246, 0xff, v4
	v_lshlrev_b32_e32 v246, 6, v246
	v_and_b32_e32 v4, 0xffffff00, v4
	v_lshlrev_b64 v[4:5], 7, v[4:5]
	v_or_b32_e32 v4, v4, v246
	v_lshl_add_u64 v[4:5], s[6:7], 0, v[4:5]
	s_waitcnt lgkmcnt(0)
	v_cvt_pk_bf16_f32 v2, v2, v3
	v_cvt_pk_bf16_f32 v3, v6, v7
	v_lshl_add_u64 v[4:5], v[4:5], 0, v[176:177]
	global_store_dwordx4 v[4:5], v[0:3], off
	s_barrier
	s_branch .LBB0_331

; DI unsigned pk_bf16(float a, float b) { bf2_t v = __builtin_convertvector((f2_t){a, b}, bf2_t); return __builtin_bit_cast(unsigned, v); }
; DI void transpose_tile(const float* __restrict__ src, int Nsrc, int K, bf16_t* __restrict__ dst, int mode, int k0, int n0, float* tile  ) {
;     ...
;     __syncthreads();
;     const int n = tid >> 3, ks = (tid & 7) * 8;
;     u32x4 w;
;     w.x = pk_bf16(tile[(ks + 0) * 65 + n], tile[(ks + 1) * 65 + n]);
;     w.y = pk_bf16(tile[(ks + 2) * 65 + n], tile[(ks + 3) * 65 + n]);
;     w.z = pk_bf16(tile[(ks + 4) * 65 + n], tile[(ks + 5) * 65 + n]);
;     w.w = pk_bf16(tile[(ks + 6) * 65 + n], tile[(ks + 7) * 65 + n]);
;     *(u32x4*)(dst + ((size_t)((n0 >> 8) * (K >> 6) + (k0 >> 6)) * 256 + (n0 & 255) + n) * 64 + ks) = w;
;     __syncthreads();
.LBB0_367:
	s_or_b64 exec, exec, s[6:7]
	v_add_u32_e32 v4, 0x2080, v10
	s_mul_hi_i32 s7, s14, 0xb00000
	s_mul_i32 s14, s14, 0xb00000
	s_waitcnt vmcnt(0)
	ds_write2_b32 v4, v0, v1 offset1:1
	v_add_u32_e32 v0, 0x2088, v10
	s_add_u32 s6, s90, s14
	ds_write2_b32 v0, v2, v3 offset1:1
	v_lshlrev_b32_e32 v0, 3, v8
	v_ashrrev_i32_e32 v4, 3, v8
	v_and_b32_e32 v10, 56, v0
	s_addc_u32 s7, s91, s7
	s_lshl_b32 s12, s12, 2
	v_mul_u32_u24_e32 v0, 0x104, v10
	v_lshlrev_b32_e32 v1, 2, v4
	s_and_b32 s12, s12, -16
	v_add3_u32 v5, 0, v0, v1
	s_add_i32 s14, s12, s4
	s_waitcnt lgkmcnt(0)
	s_barrier
	ds_read2_b32 v[0:1], v5 offset1:65
	ds_read2_b32 v[2:3], v5 offset0:130 offset1:195
	v_add_u32_e32 v5, 0x400, v5
	s_ashr_i32 s15, s14, 31
	ds_read2_b32 v[6:7], v5 offset0:4 offset1:69
	ds_read2_b32 v[8:9], v5 offset0:134 offset1:199
	s_lshl_b64 s[14:15], s[14:15], 8
	s_and_b32 s4, s13, 0xc0
	s_or_b32 s14, s14, s4
	v_ashrrev_i32_e32 v5, 31, v4
	v_lshl_add_u64 v[4:5], s[14:15], 0, v[4:5]
	v_and_b32_e32 v246, 0xff, v4
	v_lshlrev_b32_e32 v246, 6, v246
	v_and_b32_e32 v4, 0xffffff00, v4
	v_lshlrev_b64 v[4:5], 7, v[4:5]
	v_or_b32_e32 v4, v4, v246
	v_lshl_add_u64 v[4:5], s[6:7], 0, v[4:5]
	v_lshlrev_b32_e32 v176, 1, v10
	v_and_b32_e32 v245, 64, v176
	v_and_b32_e32 v176, 48, v176
	v_lshl_or_b32 v176, v245, 8, v176
	s_waitcnt lgkmcnt(3)
	v_cvt_pk_bf16_f32 v0, v0, v1
	s_waitcnt lgkmcnt(2)
	v_cvt_pk_bf16_f32 v1, v2, v3
	s_waitcnt lgkmcnt(1)
	v_cvt_pk_bf16_f32 v2, v6, v7
	s_waitcnt lgkmcnt(0)
	v_cvt_pk_bf16_f32 v3, v8, v9
	v_lshl_add_u64 v[4:5], v[4:5], 0, v[176:177]
	global_store_dwordx4 v[4:5], v[0:3], off
	s_barrier

; DI unsigned pk_bf16(float a, float b) { bf2_t v = __builtin_convertvector((f2_t){a, b}, bf2_t); return __builtin_bit_cast(unsigned, v); }
; DI int tid_() { int t = threadIdx.x; asm volatile("" : "+v"(t)); return t; }
; DI void transpose_tile(const float* __restrict__ src, int Nsrc, int K, bf16_t* __restrict__ dst, int mode, int k0, int n0, float* tile  ) {
;     const int tid = tid_();
;     const int n4 = (tid & 15) * 4;
;     const int c = colmap(mode, n0 + n4);
; #pragma unroll
;     for (int i = 0; i < 2; ++i) {
;         const int kk = (tid >> 4) + 32 * i;
;         f32x4 v = {0.f, 0.f, 0.f, 0.f};
;         if (c >= 0) v = *(const f32x4*)(src + (size_t)(k0 + kk) * Nsrc + c);
;         tile[kk * 65 + n4] = v[0]; tile[kk * 65 + n4 + 1] = v[1]; tile[kk * 65 + n4 + 2] = v[2]; tile[kk * 65 + n4 + 3] = v[3];
;     }
;     __syncthreads();
;     const int n = tid >> 3, ks = (tid & 7) * 8;
;     u32x4 w;
;     w.x = pk_bf16(tile[(ks + 0) * 65 + n], tile[(ks + 1) * 65 + n]);
;     w.y = pk_bf16(tile[(ks + 2) * 65 + n], tile[(ks + 3) * 65 + n]);
;     w.z = pk_bf16(tile[(ks + 4) * 65 + n], tile[(ks + 5) * 65 + n]);
;     w.w = pk_bf16(tile[(ks + 6) * 65 + n], tile[(ks + 7) * 65 + n]);
;     *(u32x4*)(dst + ((size_t)((n0 >> 8) * (K >> 6) + (k0 >> 6)) * 256 + (n0 & 255) + n) * 64 + ks) = w;
;     __syncthreads();
; DI void prep_weights(const Params& P, unsigned char* smem, int L, int vb, int nvb, int part  ) {
;     ...
;         else if (idx < E5) { const int t = idx - E4; const int kt = t / 16, nt = t % 16;
;             transpose_tile(P.ple_w_gate + (size_t)L * D * D, D, D, (bf16_t*)(ws + OFF_WG + L * SZ_WSQ), 0, kt * 64, nt * 64, tile); }
;         else { const int t = idx - E5; const int kt = t / 16, nt = t % 16;
;             transpose_tile(P.ple_w_proj + (size_t)L * PLE * D, D, PLE, (bf16_t*)(ws + OFF_WP + L * SZ_WP), 0, kt * 64, nt * 64, tile); }
.LBB0_372:
	s_andn2_b64 vcc, exec, s[6:7]
	s_cbranch_vccnz .LBB0_369
	s_cmpk_gt_i32 s11, 0xaff
	s_mov_b64 s[6:7], -1
	s_cbranch_scc0 .LBB0_401
	s_cmpk_gt_u32 s11, 0x107f
	s_cbranch_scc0 .LBB0_398
	s_cmpk_gt_u32 s11, 0x143f
	s_cbranch_scc0 .LBB0_385
	s_cmpk_gt_u32 s11, 0x153f
	s_cbranch_scc0 .LBB0_382
	s_and_b32 s14, s10, 0x3c0
	s_cmpk_gt_u32 s11, 0x163f
	s_cbranch_scc0 .LBB0_379
	v_mov_b32_e32 v9, v223
	s_and_b32 s4, s9, 0x7fffffc0
	s_addk_i32 s4, 0xa700
	v_lshlrev_b32_e32 v0, 2, v9
	v_and_b32_e32 v10, 60, v0
	v_ashrrev_i32_e32 v11, 4, v9
	v_or_b32_e32 v0, s14, v10
	v_readlane_b32 s16, v250, 58
	v_add_u32_e32 v6, s4, v11
	v_lshlrev_b32_e32 v176, 2, v0
	v_readlane_b32 s26, v249, 4
	v_readlane_b32 s27, v249, 5
	v_ashrrev_i32_e32 v7, 31, v6
	v_lshlrev_b64 v[0:1], 12, v[6:7]
	v_lshl_add_u64 v[4:5], s[26:27], 0, v[176:177]
	v_add_u32_e32 v6, 32, v6
	v_lshl_add_u64 v[0:1], v[4:5], 0, v[0:1]
	v_ashrrev_i32_e32 v7, 31, v6
	global_load_dwordx4 v[0:3], v[0:1], off
	v_lshlrev_b64 v[6:7], 12, v[6:7]
	v_lshl_add_u64 v[4:5], v[4:5], 0, v[6:7]
	global_load_dwordx4 v[4:7], v[4:5], off
	v_ashrrev_i32_e32 v8, 3, v9
	v_lshlrev_b32_e32 v9, 3, v9
	s_movk_i32 s0, 0x104
	v_and_b32_e32 v12, 56, v9
	s_and_b32 s6, s11, 12
	s_lshr_b32 s4, s4, 6
	v_mul_lo_u32 v11, v11, s0
	v_lshlrev_b32_e32 v13, 2, v8
	v_lshlrev_b32_e32 v10, 2, v10
	v_mul_u32_u24_e32 v14, 0x104, v12
	s_add_i32 s4, s4, s6
	v_add3_u32 v10, 0, v10, v11
	v_add3_u32 v11, 0, v14, v13
	s_and_b32 s15, s10, 0xc0
	s_lshl_b64 s[6:7], s[4:5], 8
	v_add_u32_e32 v13, 0x2080, v10
	v_add_u32_e32 v14, 0x2088, v10
	v_add_u32_e32 v15, 0x400, v11
	v_ashrrev_i32_e32 v9, 31, v8
	s_or_b32 s6, s6, s15
	v_lshl_add_u64 v[8:9], s[6:7], 0, v[8:9]
	v_readlane_b32 s6, v250, 14
	v_and_b32_e32 v246, 0xff, v8
	v_lshlrev_b32_e32 v246, 6, v246
	v_and_b32_e32 v8, 0xffffff00, v8
	v_lshlrev_b64 v[8:9], 7, v[8:9]
	v_or_b32_e32 v8, v8, v246
	v_readlane_b32 s7, v250, 15
	v_lshlrev_b32_e32 v176, 1, v12
	v_and_b32_e32 v245, 64, v176
	v_and_b32_e32 v176, 48, v176
	v_lshl_or_b32 v176, v245, 8, v176
	v_readlane_b32 s17, v250, 59
	v_lshl_add_u64 v[8:9], s[6:7], 0, v[8:9]
	v_lshl_add_u64 v[8:9], v[8:9], 0, v[176:177]
	v_readlane_b32 s18, v250, 60
	v_readlane_b32 s19, v250, 61
	v_readlane_b32 s20, v250, 62
	v_readlane_b32 s21, v250, 63
	v_readlane_b32 s22, v249, 0
	v_readlane_b32 s23, v249, 1
	v_readlane_b32 s24, v249, 2
	v_readlane_b32 s25, v249, 3
	v_readlane_b32 s28, v249, 6
	v_readlane_b32 s29, v249, 7
	v_readlane_b32 s30, v249, 8
	v_readlane_b32 s31, v249, 9
	s_mov_b64 s[6:7], 0
	s_waitcnt vmcnt(1)
	ds_write2_b32 v10, v0, v1 offset1:1
	ds_write2_b32 v10, v2, v3 offset0:2 offset1:3
	s_waitcnt vmcnt(0)
	ds_write2_b32 v13, v4, v5 offset1:1
	ds_write2_b32 v14, v6, v7 offset1:1
	s_waitcnt lgkmcnt(0)
	s_barrier
	ds_read2_b32 v[0:1], v11 offset1:65
	ds_read2_b32 v[2:3], v11 offset0:130 offset1:195
	ds_read2_b32 v[4:5], v15 offset0:4 offset1:69
	ds_read2_b32 v[6:7], v15 offset0:134 offset1:199
	s_waitcnt lgkmcnt(3)
	v_cvt_pk_bf16_f32 v0, v0, v1
	s_waitcnt lgkmcnt(2)
	v_cvt_pk_bf16_f32 v1, v2, v3
	s_waitcnt lgkmcnt(1)
	v_cvt_pk_bf16_f32 v2, v4, v5
	s_waitcnt lgkmcnt(0)
	v_cvt_pk_bf16_f32 v3, v6, v7
	global_store_dwordx4 v[8:9], v[0:3], off
	s_barrier
.LBB0_379:
	s_andn2_b64 vcc, exec, s[6:7]
	s_cbranch_vccnz .LBB0_381
	v_mov_b32_e32 v9, v223
	s_and_b32 s4, s9, 0x7fc0
	s_addk_i32 s4, 0xab00
	v_lshlrev_b32_e32 v0, 2, v9
	v_and_b32_e32 v10, 60, v0
	v_ashrrev_i32_e32 v11, 4, v9
	v_or_b32_e32 v0, s14, v10
	v_readlane_b32 s16, v250, 58
	v_add_u32_e32 v6, s4, v11
	v_lshlrev_b32_e32 v176, 2, v0
	v_readlane_b32 s28, v249, 6
	v_readlane_b32 s29, v249, 7
	v_ashrrev_i32_e32 v7, 31, v6
	v_lshlrev_b64 v[0:1], 12, v[6:7]
	v_lshl_add_u64 v[4:5], s[28:29], 0, v[176:177]
	v_add_u32_e32 v6, 32, v6
	v_lshl_add_u64 v[0:1], v[4:5], 0, v[0:1]
	v_ashrrev_i32_e32 v7, 31, v6
	global_load_dwordx4 v[0:3], v[0:1], off
	v_lshlrev_b64 v[6:7], 12, v[6:7]
	v_lshl_add_u64 v[4:5], v[4:5], 0, v[6:7]
	global_load_dwordx4 v[4:7], v[4:5], off
	v_ashrrev_i32_e32 v8, 3, v9
	v_lshlrev_b32_e32 v9, 3, v9
	s_movk_i32 s0, 0x104
	v_and_b32_e32 v12, 56, v9
	s_and_b32 s6, s9, 48
	s_lshr_b32 s4, s4, 6
	v_mul_lo_u32 v11, v11, s0
	v_lshlrev_b32_e32 v13, 2, v8
	v_lshlrev_b32_e32 v10, 2, v10
	v_mul_u32_u24_e32 v14, 0x104, v12
	s_add_i32 s4, s4, s6
	v_add3_u32 v10, 0, v10, v11
	v_add3_u32 v11, 0, v14, v13
	s_and_b32 s14, s10, 0xc0
	s_lshl_b64 s[6:7], s[4:5], 8
	v_add_u32_e32 v13, 0x2080, v10
	v_add_u32_e32 v14, 0x2088, v10
	v_add_u32_e32 v15, 0x400, v11
	v_ashrrev_i32_e32 v9, 31, v8
	s_or_b32 s6, s6, s14
	v_lshl_add_u64 v[8:9], s[6:7], 0, v[8:9]
	v_readlane_b32 s6, v250, 12
	v_and_b32_e32 v246, 0xff, v8
	v_lshlrev_b32_e32 v246, 6, v246
	v_and_b32_e32 v8, 0xffffff00, v8
	v_lshlrev_b64 v[8:9], 7, v[8:9]
	v_or_b32_e32 v8, v8, v246
	v_readlane_b32 s7, v250, 13
	v_lshlrev_b32_e32 v176, 1, v12
	v_and_b32_e32 v245, 64, v176
	v_and_b32_e32 v176, 48, v176
	v_lshl_or_b32 v176, v245, 8, v176
	v_readlane_b32 s17, v250, 59
	v_lshl_add_u64 v[8:9], s[6:7], 0, v[8:9]
	v_lshl_add_u64 v[8:9], v[8:9], 0, v[176:177]
	v_readlane_b32 s18, v250, 60
	v_readlane_b32 s19, v250, 61
	v_readlane_b32 s20, v250, 62
	v_readlane_b32 s21, v250, 63
	v_readlane_b32 s22, v249, 0
	v_readlane_b32 s23, v249, 1
	v_readlane_b32 s24, v249, 2
	v_readlane_b32 s25, v249, 3
	v_readlane_b32 s26, v249, 4
	v_readlane_b32 s27, v249, 5
	v_readlane_b32 s30, v249, 8
	v_readlane_b32 s31, v249, 9
	s_waitcnt vmcnt(1)
	ds_write2_b32 v10, v0, v1 offset1:1
	ds_write2_b32 v10, v2, v3 offset0:2 offset1:3
	s_waitcnt vmcnt(0)
	ds_write2_b32 v13, v4, v5 offset1:1
	ds_write2_b32 v14, v6, v7 offset1:1
	s_waitcnt lgkmcnt(0)
	s_barrier
	ds_read2_b32 v[0:1], v11 offset1:65
	ds_read2_b32 v[2:3], v11 offset0:130 offset1:195
	ds_read2_b32 v[4:5], v15 offset0:4 offset1:69
	ds_read2_b32 v[6:7], v15 offset0:134 offset1:199
	s_waitcnt lgkmcnt(3)
	v_cvt_pk_bf16_f32 v0, v0, v1
	s_waitcnt lgkmcnt(2)
	v_cvt_pk_bf16_f32 v1, v2, v3
	s_waitcnt lgkmcnt(1)
	v_cvt_pk_bf16_f32 v2, v4, v5
	s_waitcnt lgkmcnt(0)
	v_cvt_pk_bf16_f32 v3, v6, v7
	global_store_dwordx4 v[8:9], v[0:3], off
	s_barrier

; DI unsigned pk_bf16(float a, float b) { bf2_t v = __builtin_convertvector((f2_t){a, b}, bf2_t); return __builtin_bit_cast(unsigned, v); }
; DI int tid_() { int t = threadIdx.x; asm volatile("" : "+v"(t)); return t; }
; DI void transpose_tile(const float* __restrict__ src, int Nsrc, int K, bf16_t* __restrict__ dst, int mode, int k0, int n0, float* tile  ) {
;     const int tid = tid_();
;     const int n4 = (tid & 15) * 4;
;     const int c = colmap(mode, n0 + n4);
; #pragma unroll
;     for (int i = 0; i < 2; ++i) {
;         const int kk = (tid >> 4) + 32 * i;
;         f32x4 v = {0.f, 0.f, 0.f, 0.f};
;         if (c >= 0) v = *(const f32x4*)(src + (size_t)(k0 + kk) * Nsrc + c);
;         tile[kk * 65 + n4] = v[0]; tile[kk * 65 + n4 + 1] = v[1]; tile[kk * 65 + n4 + 2] = v[2]; tile[kk * 65 + n4 + 3] = v[3];
;     }
;     __syncthreads();
;     const int n = tid >> 3, ks = (tid & 7) * 8;
;     u32x4 w;
;     w.x = pk_bf16(tile[(ks + 0) * 65 + n], tile[(ks + 1) * 65 + n]);
;     w.y = pk_bf16(tile[(ks + 2) * 65 + n], tile[(ks + 3) * 65 + n]);
;     w.z = pk_bf16(tile[(ks + 4) * 65 + n], tile[(ks + 5) * 65 + n]);
;     w.w = pk_bf16(tile[(ks + 6) * 65 + n], tile[(ks + 7) * 65 + n]);
;     *(u32x4*)(dst + ((size_t)((n0 >> 8) * (K >> 6) + (k0 >> 6)) * 256 + (n0 & 255) + n) * 64 + ks) = w;
;     __syncthreads();
; DI void prep_weights(const Params& P, unsigned char* smem, int L, int vb, int nvb, int part  ) {
;     ...
;         else if (idx < E4) { const int t = idx - E3; const int kt = t / 16, nt = t % 16;
;             transpose_tile(P.mix_w_out + (size_t)L * D * D, D, D, (bf16_t*)(ws + OFF_WOUT + L * SZ_WSQ), 0, kt * 64, nt * 64, tile); }
.LBB0_382:
	s_andn2_b64 vcc, exec, s[6:7]
	s_cbranch_vccnz .LBB0_384
	v_mov_b32_e32 v9, v223
	s_and_b32 s4, s9, 0x7fc0
	s_addk_i32 s4, 0xaf00
	v_lshlrev_b32_e32 v0, 2, v9
	s_and_b32 s6, s10, 0x3c0
	v_and_b32_e32 v10, 60, v0
	v_ashrrev_i32_e32 v11, 4, v9
	v_or_b32_e32 v0, s6, v10
	v_readlane_b32 s16, v250, 58
	v_add_u32_e32 v6, s4, v11
	v_lshlrev_b32_e32 v176, 2, v0
	v_readlane_b32 s24, v249, 2
	v_readlane_b32 s25, v249, 3
	v_ashrrev_i32_e32 v7, 31, v6
	v_lshlrev_b64 v[0:1], 12, v[6:7]
	v_lshl_add_u64 v[4:5], s[24:25], 0, v[176:177]
	v_add_u32_e32 v6, 32, v6
	v_lshl_add_u64 v[0:1], v[4:5], 0, v[0:1]
	v_ashrrev_i32_e32 v7, 31, v6
	global_load_dwordx4 v[0:3], v[0:1], off
	v_lshlrev_b64 v[6:7], 12, v[6:7]
	v_lshl_add_u64 v[4:5], v[4:5], 0, v[6:7]
	global_load_dwordx4 v[4:7], v[4:5], off
	v_ashrrev_i32_e32 v8, 3, v9
	v_lshlrev_b32_e32 v9, 3, v9
	s_movk_i32 s0, 0x104
	v_and_b32_e32 v12, 56, v9
	s_and_b32 s6, s9, 48
	s_lshr_b32 s4, s4, 6
	v_mul_lo_u32 v11, v11, s0
	v_lshlrev_b32_e32 v13, 2, v8
	v_lshlrev_b32_e32 v10, 2, v10
	v_mul_u32_u24_e32 v14, 0x104, v12
	s_add_i32 s4, s4, s6
	v_add3_u32 v10, 0, v10, v11
	v_add3_u32 v11, 0, v14, v13
	s_and_b32 s14, s10, 0xc0
	s_lshl_b64 s[6:7], s[4:5], 8
	v_add_u32_e32 v13, 0x2080, v10
	v_add_u32_e32 v14, 0x2088, v10
	v_add_u32_e32 v15, 0x400, v11
	v_ashrrev_i32_e32 v9, 31, v8
	s_or_b32 s6, s6, s14
	v_lshl_add_u64 v[8:9], s[6:7], 0, v[8:9]
	v_readlane_b32 s6, v250, 16
	v_and_b32_e32 v246, 0xff, v8
	v_lshlrev_b32_e32 v246, 6, v246
	v_and_b32_e32 v8, 0xffffff00, v8
	v_lshlrev_b64 v[8:9], 7, v[8:9]
	v_or_b32_e32 v8, v8, v246
	v_readlane_b32 s7, v250, 17
	v_lshlrev_b32_e32 v176, 1, v12
	v_and_b32_e32 v245, 64, v176
	v_and_b32_e32 v176, 48, v176
	v_lshl_or_b32 v176, v245, 8, v176
	v_readlane_b32 s17, v250, 59
	v_lshl_add_u64 v[8:9], s[6:7], 0, v[8:9]
	v_lshl_add_u64 v[8:9], v[8:9], 0, v[176:177]
	v_readlane_b32 s18, v250, 60
	v_readlane_b32 s19, v250, 61
	v_readlane_b32 s20, v250, 62
	v_readlane_b32 s21, v250, 63
	v_readlane_b32 s22, v249, 0
	v_readlane_b32 s23, v249, 1
	v_readlane_b32 s26, v249, 4
	v_readlane_b32 s27, v249, 5
	v_readlane_b32 s28, v249, 6
	v_readlane_b32 s29, v249, 7
	v_readlane_b32 s30, v249, 8
	v_readlane_b32 s31, v249, 9
	s_waitcnt vmcnt(1)
	ds_write2_b32 v10, v0, v1 offset1:1
	ds_write2_b32 v10, v2, v3 offset0:2 offset1:3
	s_waitcnt vmcnt(0)
	ds_write2_b32 v13, v4, v5 offset1:1
	ds_write2_b32 v14, v6, v7 offset1:1
	s_waitcnt lgkmcnt(0)
	s_barrier
	ds_read2_b32 v[0:1], v11 offset1:65
	ds_read2_b32 v[2:3], v11 offset0:130 offset1:195
	ds_read2_b32 v[4:5], v15 offset0:4 offset1:69
	ds_read2_b32 v[6:7], v15 offset0:134 offset1:199
	s_waitcnt lgkmcnt(3)
	v_cvt_pk_bf16_f32 v0, v0, v1
	s_waitcnt lgkmcnt(2)
	v_cvt_pk_bf16_f32 v1, v2, v3
	s_waitcnt lgkmcnt(1)
	v_cvt_pk_bf16_f32 v2, v4, v5
	s_waitcnt lgkmcnt(0)
	v_cvt_pk_bf16_f32 v3, v6, v7
	global_store_dwordx4 v[8:9], v[0:3], off
	s_barrier

; DI unsigned pk_bf16(float a, float b) { bf2_t v = __builtin_convertvector((f2_t){a, b}, bf2_t); return __builtin_bit_cast(unsigned, v); }
; DI void transpose_tile(const float* __restrict__ src, int Nsrc, int K, bf16_t* __restrict__ dst, int mode, int k0, int n0, float* tile  ) {
;     ...
;     __syncthreads();
;     const int n = tid >> 3, ks = (tid & 7) * 8;
;     u32x4 w;
;     w.x = pk_bf16(tile[(ks + 0) * 65 + n], tile[(ks + 1) * 65 + n]);
;     w.y = pk_bf16(tile[(ks + 2) * 65 + n], tile[(ks + 3) * 65 + n]);
;     w.z = pk_bf16(tile[(ks + 4) * 65 + n], tile[(ks + 5) * 65 + n]);
;     w.w = pk_bf16(tile[(ks + 6) * 65 + n], tile[(ks + 7) * 65 + n]);
;     *(u32x4*)(dst + ((size_t)((n0 >> 8) * (K >> 6) + (k0 >> 6)) * 256 + (n0 & 255) + n) * 64 + ks) = w;
;     __syncthreads();
.LBB0_396:
	s_or_b64 exec, exec, s[6:7]
	v_add_u32_e32 v4, 0x2080, v10
	s_waitcnt vmcnt(0)
	ds_write2_b32 v4, v0, v1 offset1:1
	v_add_u32_e32 v0, 0x2088, v10
	ds_write2_b32 v0, v2, v3 offset1:1
	v_lshlrev_b32_e32 v0, 3, v8
	v_ashrrev_i32_e32 v4, 3, v8
	v_and_b32_e32 v10, 56, v0
	v_mul_u32_u24_e32 v0, 0x104, v10
	v_lshlrev_b32_e32 v1, 2, v4
	s_lshr_b32 s6, s4, 4
	v_add3_u32 v5, 0, v0, v1
	s_and_b32 s6, s6, 0xf0
	s_waitcnt lgkmcnt(0)
	s_barrier
	ds_read2_b32 v[0:1], v5 offset1:65
	ds_read2_b32 v[2:3], v5 offset0:130 offset1:195
	v_add_u32_e32 v5, 0x400, v5
	s_add_i32 s6, s6, s13
	ds_read2_b32 v[6:7], v5 offset0:4 offset1:69
	ds_read2_b32 v[8:9], v5 offset0:134 offset1:199
	s_lshl_b32 s6, s6, 8
	s_and_b32 s4, s4, 0xc0
	s_or_b32 s4, s6, s4
	v_ashrrev_i32_e32 v5, 31, v4
	v_lshl_add_u64 v[4:5], v[4:5], 0, s[4:5]
	v_readlane_b32 s6, v250, 18
	v_and_b32_e32 v246, 0xff, v4
	v_lshlrev_b32_e32 v246, 6, v246
	v_and_b32_e32 v4, 0xffffff00, v4
	v_lshlrev_b64 v[4:5], 7, v[4:5]
	v_or_b32_e32 v4, v4, v246
	v_readlane_b32 s7, v250, 19
	v_lshlrev_b32_e32 v176, 1, v10
	v_and_b32_e32 v245, 64, v176
	v_and_b32_e32 v176, 48, v176
	v_lshl_or_b32 v176, v245, 8, v176
	s_waitcnt lgkmcnt(3)
	v_cvt_pk_bf16_f32 v0, v0, v1
	v_lshl_add_u64 v[4:5], s[6:7], 0, v[4:5]
	s_waitcnt lgkmcnt(2)
	v_cvt_pk_bf16_f32 v1, v2, v3
	s_waitcnt lgkmcnt(1)
	v_cvt_pk_bf16_f32 v2, v6, v7
	s_waitcnt lgkmcnt(0)
	v_cvt_pk_bf16_f32 v3, v8, v9
	v_lshl_add_u64 v[4:5], v[4:5], 0, v[176:177]
	global_store_dwordx4 v[4:5], v[0:3], off
	s_barrier

; DI unsigned pk_bf16(float a, float b) { bf2_t v = __builtin_convertvector((f2_t){a, b}, bf2_t); return __builtin_bit_cast(unsigned, v); }
; DI int tid_() { int t = threadIdx.x; asm volatile("" : "+v"(t)); return t; }
; DI void transpose_tile(const float* __restrict__ src, int Nsrc, int K, bf16_t* __restrict__ dst, int mode, int k0, int n0, float* tile  ) {
;     const int tid = tid_();
;     const int n4 = (tid & 15) * 4;
;     const int c = colmap(mode, n0 + n4);
; #pragma unroll
;     for (int i = 0; i < 2; ++i) {
;         const int kk = (tid >> 4) + 32 * i;
;         f32x4 v = {0.f, 0.f, 0.f, 0.f};
;         if (c >= 0) v = *(const f32x4*)(src + (size_t)(k0 + kk) * Nsrc + c);
;         tile[kk * 65 + n4] = v[0]; tile[kk * 65 + n4 + 1] = v[1]; tile[kk * 65 + n4 + 2] = v[2]; tile[kk * 65 + n4 + 3] = v[3];
;     }
;     __syncthreads();
;     const int n = tid >> 3, ks = (tid & 7) * 8;
;     u32x4 w;
;     w.x = pk_bf16(tile[(ks + 0) * 65 + n], tile[(ks + 1) * 65 + n]);
;     w.y = pk_bf16(tile[(ks + 2) * 65 + n], tile[(ks + 3) * 65 + n]);
;     w.z = pk_bf16(tile[(ks + 4) * 65 + n], tile[(ks + 5) * 65 + n]);
;     w.w = pk_bf16(tile[(ks + 6) * 65 + n], tile[(ks + 7) * 65 + n]);
;     *(u32x4*)(dst + ((size_t)((n0 >> 8) * (K >> 6) + (k0 >> 6)) * 256 + (n0 & 255) + n) * 64 + ks) = w;
;     __syncthreads();
; DI void prep_weights(const Params& P, unsigned char* smem, int L, int vb, int nvb, int part  ) {
;     ...
;         else if (idx < E2) { const int q = idx - E1; const int j = L * 2 + q / T_W2, t = q % T_W2; const int kt = t / 16, nt = t % 16;
;             transpose_tile(P.ffn_w_out + (size_t)j * DFF * D, D, DFF, (bf16_t*)(ws + OFF_W2 + j * SZ_W2), 0, kt * 64, nt * 64, tile); }
.LBB0_398:
	s_andn2_b64 vcc, exec, s[6:7]
	s_cbranch_vccnz .LBB0_400
	s_add_i32 s4, s11, 0xfffff240
	s_cmpk_lt_u32 s12, 0x2c0
	s_cselect_b32 s4, s12, s4
	s_cmpk_gt_u32 s12, 0x2bf
	v_readlane_b32 s16, v249, 53
	s_cselect_b32 s6, 0xb00000, 0
	v_readlane_b32 s26, v249, 63
	s_cselect_b32 s12, 0x580000, 0
	v_readlane_b32 s27, v248, 0
	s_add_u32 s6, s26, s6
	s_addc_u32 s7, s27, 0
	v_readlane_b32 s13, v250, 20
	s_add_u32 s12, s13, s12
	v_readlane_b32 s13, v250, 21
	v_mov_b32_e32 v9, v223
	s_addc_u32 s13, s13, 0
	s_lshl_b32 s14, s4, 2
	s_lshl_b32 s15, s4, 6
	s_and_b32 s14, s14, 0xfc0
	v_lshlrev_b32_e32 v0, 2, v9
	s_and_b32 s16, s15, 0x3c0
	v_and_b32_e32 v10, 60, v0
	v_ashrrev_i32_e32 v11, 4, v9
	v_or_b32_e32 v0, s16, v10
	v_add_u32_e32 v6, s14, v11
	v_lshlrev_b32_e32 v176, 2, v0
	v_ashrrev_i32_e32 v7, 31, v6
	v_lshl_add_u64 v[4:5], s[6:7], 0, v[176:177]
	v_lshlrev_b64 v[0:1], 12, v[6:7]
	v_add_u32_e32 v6, 32, v6
	v_lshl_add_u64 v[0:1], v[4:5], 0, v[0:1]
	v_ashrrev_i32_e32 v7, 31, v6
	global_load_dwordx4 v[0:3], v[0:1], off
	v_lshlrev_b64 v[6:7], 12, v[6:7]
	v_lshl_add_u64 v[4:5], v[4:5], 0, v[6:7]
	global_load_dwordx4 v[4:7], v[4:5], off
	v_ashrrev_i32_e32 v8, 3, v9
	v_lshlrev_b32_e32 v9, 3, v9
	s_movk_i32 s0, 0x104
	v_and_b32_e32 v12, 56, v9
	s_bfe_u32 s6, s15, 0x20008
	v_mul_lo_u32 v11, v11, s0
	v_lshlrev_b32_e32 v13, 2, v8
	v_lshlrev_b32_e32 v10, 2, v10
	v_mul_u32_u24_e32 v14, 0x104, v12
	s_bfe_u32 s4, s4, 0x60004
	s_mul_i32 s6, s6, 44
	v_add3_u32 v10, 0, v10, v11
	v_add3_u32 v11, 0, v14, v13
	s_add_i32 s6, s6, s4
	v_add_u32_e32 v13, 0x2080, v10
	v_add_u32_e32 v14, 0x2088, v10
	v_add_u32_e32 v15, 0x400, v11
	s_and_b32 s7, s15, 0xc0
	s_lshl_b32 s4, s6, 8
	v_ashrrev_i32_e32 v9, 31, v8
	s_or_b32 s4, s4, s7
	v_lshl_add_u64 v[8:9], v[8:9], 0, s[4:5]
	v_and_b32_e32 v246, 0xff, v8
	v_lshlrev_b32_e32 v246, 6, v246
	v_and_b32_e32 v8, 0xffffff00, v8
	v_lshlrev_b64 v[8:9], 7, v[8:9]
	v_or_b32_e32 v8, v8, v246
	v_lshlrev_b32_e32 v176, 1, v12
	v_and_b32_e32 v245, 64, v176
	v_and_b32_e32 v176, 48, v176
	v_lshl_or_b32 v176, v245, 8, v176
	v_lshl_add_u64 v[8:9], s[12:13], 0, v[8:9]
	v_lshl_add_u64 v[8:9], v[8:9], 0, v[176:177]
	v_readlane_b32 s17, v249, 54
	v_readlane_b32 s18, v249, 55
	v_readlane_b32 s19, v249, 56
	v_readlane_b32 s20, v249, 57
	v_readlane_b32 s21, v249, 58
	v_readlane_b32 s22, v249, 59
	v_readlane_b32 s23, v249, 60
	v_readlane_b32 s24, v249, 61
	v_readlane_b32 s25, v249, 62
	v_readlane_b32 s28, v248, 1
	v_readlane_b32 s29, v248, 2
	v_readlane_b32 s30, v248, 3
	v_readlane_b32 s31, v248, 4
	s_waitcnt vmcnt(1)
	ds_write2_b32 v10, v0, v1 offset1:1
	ds_write2_b32 v10, v2, v3 offset0:2 offset1:3
	s_waitcnt vmcnt(0)
	ds_write2_b32 v13, v4, v5 offset1:1
	ds_write2_b32 v14, v6, v7 offset1:1
	s_waitcnt lgkmcnt(0)
	s_barrier
	ds_read2_b32 v[0:1], v11 offset1:65
	ds_read2_b32 v[2:3], v11 offset0:130 offset1:195
	ds_read2_b32 v[4:5], v15 offset0:4 offset1:69
	ds_read2_b32 v[6:7], v15 offset0:134 offset1:199
	s_waitcnt lgkmcnt(3)
	v_cvt_pk_bf16_f32 v0, v0, v1
	s_waitcnt lgkmcnt(2)
	v_cvt_pk_bf16_f32 v1, v2, v3
	s_waitcnt lgkmcnt(1)
	v_cvt_pk_bf16_f32 v2, v4, v5
	s_waitcnt lgkmcnt(0)
	v_cvt_pk_bf16_f32 v3, v6, v7
	global_store_dwordx4 v[8:9], v[0:3], off
	s_barrier

; DI unsigned pk_bf16(float a, float b) { bf2_t v = __builtin_convertvector((f2_t){a, b}, bf2_t); return __builtin_bit_cast(unsigned, v); }
; DI int tid_() { int t = threadIdx.x; asm volatile("" : "+v"(t)); return t; }
; DI void transpose_tile(const float* __restrict__ src, int Nsrc, int K, bf16_t* __restrict__ dst, int mode, int k0, int n0, float* tile  ) {
;     const int tid = tid_();
;     const int n4 = (tid & 15) * 4;
;     const int c = colmap(mode, n0 + n4);
; #pragma unroll
;     for (int i = 0; i < 2; ++i) {
;         const int kk = (tid >> 4) + 32 * i;
;         f32x4 v = {0.f, 0.f, 0.f, 0.f};
;         if (c >= 0) v = *(const f32x4*)(src + (size_t)(k0 + kk) * Nsrc + c);
;         tile[kk * 65 + n4] = v[0]; tile[kk * 65 + n4 + 1] = v[1]; tile[kk * 65 + n4 + 2] = v[2]; tile[kk * 65 + n4 + 3] = v[3];
;     }
;     __syncthreads();
;     const int n = tid >> 3, ks = (tid & 7) * 8;
;     u32x4 w;
;     w.x = pk_bf16(tile[(ks + 0) * 65 + n], tile[(ks + 1) * 65 + n]);
;     w.y = pk_bf16(tile[(ks + 2) * 65 + n], tile[(ks + 3) * 65 + n]);
;     w.z = pk_bf16(tile[(ks + 4) * 65 + n], tile[(ks + 5) * 65 + n]);
;     w.w = pk_bf16(tile[(ks + 6) * 65 + n], tile[(ks + 7) * 65 + n]);
;     *(u32x4*)(dst + ((size_t)((n0 >> 8) * (K >> 6) + (k0 >> 6)) * 256 + (n0 & 255) + n) * 64 + ks) = w;
;     __syncthreads();
; DI void prep_weights(const Params& P, unsigned char* smem, int L, int vb, int nvb, int part  ) {
;     ...
;         else if (idx < E5) { const int t = idx - E4; const int kt = t / 16, nt = t % 16;
;             transpose_tile(P.ple_w_gate + (size_t)L * D * D, D, D, (bf16_t*)(ws + OFF_WG + L * SZ_WSQ), 0, kt * 64, nt * 64, tile); }
;         else { const int t = idx - E5; const int kt = t / 16, nt = t % 16;
;             transpose_tile(P.ple_w_proj + (size_t)L * PLE * D, D, PLE, (bf16_t*)(ws + OFF_WP + L * SZ_WP), 0, kt * 64, nt * 64, tile); }
.LBB0_410:
	s_cmpk_gt_i32 s11, 0xaff
	s_mov_b64 s[6:7], -1
	s_cbranch_scc0 .LBB0_438
	s_cmpk_gt_u32 s11, 0x107f
	s_cbranch_scc0 .LBB0_435
	s_cmpk_gt_u32 s11, 0x143f
	s_cbranch_scc0 .LBB0_422
	s_cmpk_gt_u32 s11, 0x153f
	s_cbranch_scc0 .LBB0_419
	s_and_b32 s12, s9, 0x3c0
	s_cmpk_gt_u32 s11, 0x163f
	s_cbranch_scc0 .LBB0_416
	v_mov_b32_e32 v9, v223
	s_and_b32 s4, s10, 0x7fffffc0
	s_addk_i32 s4, 0xa700
	v_lshlrev_b32_e32 v0, 2, v9
	v_and_b32_e32 v10, 60, v0
	v_ashrrev_i32_e32 v11, 4, v9
	v_or_b32_e32 v0, s12, v10
	v_readlane_b32 s0, v250, 54
	v_add_u32_e32 v6, s4, v11
	v_lshlrev_b32_e32 v176, 2, v0
	v_readlane_b32 s1, v250, 55
	v_ashrrev_i32_e32 v7, 31, v6
	v_lshlrev_b64 v[0:1], 12, v[6:7]
	v_lshl_add_u64 v[4:5], s[0:1], 0, v[176:177]
	v_add_u32_e32 v6, 32, v6
	v_lshl_add_u64 v[0:1], v[4:5], 0, v[0:1]
	v_ashrrev_i32_e32 v7, 31, v6
	global_load_dwordx4 v[0:3], v[0:1], off
	v_lshlrev_b64 v[6:7], 12, v[6:7]
	v_lshl_add_u64 v[4:5], v[4:5], 0, v[6:7]
	global_load_dwordx4 v[4:7], v[4:5], off
	v_ashrrev_i32_e32 v8, 3, v9
	v_lshlrev_b32_e32 v9, 3, v9
	s_movk_i32 s0, 0x104
	v_and_b32_e32 v12, 56, v9
	s_and_b32 s6, s11, 12
	s_lshr_b32 s4, s4, 6
	v_mul_lo_u32 v11, v11, s0
	v_lshlrev_b32_e32 v13, 2, v8
	v_lshlrev_b32_e32 v10, 2, v10
	v_mul_u32_u24_e32 v14, 0x104, v12
	s_add_i32 s4, s4, s6
	v_add3_u32 v10, 0, v10, v11
	v_add3_u32 v11, 0, v14, v13
	s_and_b32 s13, s9, 0xc0
	s_lshl_b64 s[6:7], s[4:5], 8
	v_add_u32_e32 v13, 0x2080, v10
	v_add_u32_e32 v14, 0x2088, v10
	v_add_u32_e32 v15, 0x400, v11
	v_ashrrev_i32_e32 v9, 31, v8
	s_or_b32 s6, s6, s13
	v_lshl_add_u64 v[8:9], s[6:7], 0, v[8:9]
	v_readlane_b32 s6, v250, 46
	v_and_b32_e32 v246, 0xff, v8
	v_lshlrev_b32_e32 v246, 6, v246
	v_and_b32_e32 v8, 0xffffff00, v8
	v_lshlrev_b64 v[8:9], 7, v[8:9]
	v_or_b32_e32 v8, v8, v246
	v_readlane_b32 s7, v250, 47
	v_lshlrev_b32_e32 v176, 1, v12
	v_and_b32_e32 v245, 64, v176
	v_and_b32_e32 v176, 48, v176
	v_lshl_or_b32 v176, v245, 8, v176
	s_waitcnt vmcnt(1)
	ds_write2_b32 v10, v0, v1 offset1:1
	ds_write2_b32 v10, v2, v3 offset0:2 offset1:3
	s_waitcnt vmcnt(0)
	ds_write2_b32 v13, v4, v5 offset1:1
	ds_write2_b32 v14, v6, v7 offset1:1
	s_waitcnt lgkmcnt(0)
	s_barrier
	ds_read2_b32 v[0:1], v11 offset1:65
	ds_read2_b32 v[2:3], v11 offset0:130 offset1:195
	ds_read2_b32 v[4:5], v15 offset0:4 offset1:69
	ds_read2_b32 v[6:7], v15 offset0:134 offset1:199
	v_lshl_add_u64 v[8:9], s[6:7], 0, v[8:9]
	v_lshl_add_u64 v[8:9], v[8:9], 0, v[176:177]
	s_waitcnt lgkmcnt(3)
	v_cvt_pk_bf16_f32 v0, v0, v1
	s_waitcnt lgkmcnt(2)
	v_cvt_pk_bf16_f32 v1, v2, v3
	s_waitcnt lgkmcnt(1)
	v_cvt_pk_bf16_f32 v2, v4, v5
	s_waitcnt lgkmcnt(0)
	v_cvt_pk_bf16_f32 v3, v6, v7
	global_store_dwordx4 v[8:9], v[0:3], off
	s_barrier
	s_mov_b64 s[6:7], 0
.LBB0_416:
	s_andn2_b64 vcc, exec, s[6:7]
	s_cbranch_vccnz .LBB0_418
	v_mov_b32_e32 v9, v223
	s_and_b32 s4, s10, 0x7fc0
	s_addk_i32 s4, 0xab00
	v_lshlrev_b32_e32 v0, 2, v9
	v_and_b32_e32 v10, 60, v0
	v_ashrrev_i32_e32 v11, 4, v9
	v_or_b32_e32 v0, s12, v10
	v_readlane_b32 s0, v250, 56
	v_add_u32_e32 v6, s4, v11
	v_lshlrev_b32_e32 v176, 2, v0
	v_readlane_b32 s1, v250, 57
	v_ashrrev_i32_e32 v7, 31, v6
	v_lshlrev_b64 v[0:1], 12, v[6:7]
	v_lshl_add_u64 v[4:5], s[0:1], 0, v[176:177]
	v_add_u32_e32 v6, 32, v6
	v_lshl_add_u64 v[0:1], v[4:5], 0, v[0:1]
	v_ashrrev_i32_e32 v7, 31, v6
	global_load_dwordx4 v[0:3], v[0:1], off
	v_lshlrev_b64 v[6:7], 12, v[6:7]
	v_lshl_add_u64 v[4:5], v[4:5], 0, v[6:7]
	global_load_dwordx4 v[4:7], v[4:5], off
	v_ashrrev_i32_e32 v8, 3, v9
	v_lshlrev_b32_e32 v9, 3, v9
	s_movk_i32 s0, 0x104
	v_and_b32_e32 v12, 56, v9
	s_and_b32 s6, s10, 48
	s_lshr_b32 s4, s4, 6
	v_mul_lo_u32 v11, v11, s0
	v_lshlrev_b32_e32 v13, 2, v8
	v_lshlrev_b32_e32 v10, 2, v10
	v_mul_u32_u24_e32 v14, 0x104, v12
	s_add_i32 s4, s4, s6
	v_add3_u32 v10, 0, v10, v11
	v_add3_u32 v11, 0, v14, v13
	s_and_b32 s12, s9, 0xc0
	s_lshl_b64 s[6:7], s[4:5], 8
	v_add_u32_e32 v13, 0x2080, v10
	v_add_u32_e32 v14, 0x2088, v10
	v_add_u32_e32 v15, 0x400, v11
	v_ashrrev_i32_e32 v9, 31, v8
	s_or_b32 s6, s6, s12
	v_lshl_add_u64 v[8:9], s[6:7], 0, v[8:9]
	v_readlane_b32 s6, v250, 48
	v_and_b32_e32 v246, 0xff, v8
	v_lshlrev_b32_e32 v246, 6, v246
	v_and_b32_e32 v8, 0xffffff00, v8
	v_lshlrev_b64 v[8:9], 7, v[8:9]
	v_or_b32_e32 v8, v8, v246
	v_readlane_b32 s7, v250, 49
	v_lshlrev_b32_e32 v176, 1, v12
	v_and_b32_e32 v245, 64, v176
	v_and_b32_e32 v176, 48, v176
	v_lshl_or_b32 v176, v245, 8, v176
	s_waitcnt vmcnt(1)
	ds_write2_b32 v10, v0, v1 offset1:1
	ds_write2_b32 v10, v2, v3 offset0:2 offset1:3
	s_waitcnt vmcnt(0)
	ds_write2_b32 v13, v4, v5 offset1:1
	ds_write2_b32 v14, v6, v7 offset1:1
	s_waitcnt lgkmcnt(0)
	s_barrier
	ds_read2_b32 v[0:1], v11 offset1:65
	ds_read2_b32 v[2:3], v11 offset0:130 offset1:195
	ds_read2_b32 v[4:5], v15 offset0:4 offset1:69
	ds_read2_b32 v[6:7], v15 offset0:134 offset1:199
	v_lshl_add_u64 v[8:9], s[6:7], 0, v[8:9]
	v_lshl_add_u64 v[8:9], v[8:9], 0, v[176:177]
	s_waitcnt lgkmcnt(3)
	v_cvt_pk_bf16_f32 v0, v0, v1
	s_waitcnt lgkmcnt(2)
	v_cvt_pk_bf16_f32 v1, v2, v3
	s_waitcnt lgkmcnt(1)
	v_cvt_pk_bf16_f32 v2, v4, v5
	s_waitcnt lgkmcnt(0)
	v_cvt_pk_bf16_f32 v3, v6, v7
	global_store_dwordx4 v[8:9], v[0:3], off
	s_barrier

; DI unsigned pk_bf16(float a, float b) { bf2_t v = __builtin_convertvector((f2_t){a, b}, bf2_t); return __builtin_bit_cast(unsigned, v); }
; DI int tid_() { int t = threadIdx.x; asm volatile("" : "+v"(t)); return t; }
; DI void transpose_tile(const float* __restrict__ src, int Nsrc, int K, bf16_t* __restrict__ dst, int mode, int k0, int n0, float* tile  ) {
;     const int tid = tid_();
;     const int n4 = (tid & 15) * 4;
;     const int c = colmap(mode, n0 + n4);
; #pragma unroll
;     for (int i = 0; i < 2; ++i) {
;         const int kk = (tid >> 4) + 32 * i;
;         f32x4 v = {0.f, 0.f, 0.f, 0.f};
;         if (c >= 0) v = *(const f32x4*)(src + (size_t)(k0 + kk) * Nsrc + c);
;         tile[kk * 65 + n4] = v[0]; tile[kk * 65 + n4 + 1] = v[1]; tile[kk * 65 + n4 + 2] = v[2]; tile[kk * 65 + n4 + 3] = v[3];
;     }
;     __syncthreads();
;     const int n = tid >> 3, ks = (tid & 7) * 8;
;     u32x4 w;
;     w.x = pk_bf16(tile[(ks + 0) * 65 + n], tile[(ks + 1) * 65 + n]);
;     w.y = pk_bf16(tile[(ks + 2) * 65 + n], tile[(ks + 3) * 65 + n]);
;     w.z = pk_bf16(tile[(ks + 4) * 65 + n], tile[(ks + 5) * 65 + n]);
;     w.w = pk_bf16(tile[(ks + 6) * 65 + n], tile[(ks + 7) * 65 + n]);
;     *(u32x4*)(dst + ((size_t)((n0 >> 8) * (K >> 6) + (k0 >> 6)) * 256 + (n0 & 255) + n) * 64 + ks) = w;
;     __syncthreads();
; DI void prep_weights(const Params& P, unsigned char* smem, int L, int vb, int nvb, int part  ) {
;     ...
;         else if (idx < E4) { const int t = idx - E3; const int kt = t / 16, nt = t % 16;
;             transpose_tile(P.mix_w_out + (size_t)L * D * D, D, D, (bf16_t*)(ws + OFF_WOUT + L * SZ_WSQ), 0, kt * 64, nt * 64, tile); }
.LBB0_419:
	s_andn2_b64 vcc, exec, s[6:7]
	s_cbranch_vccnz .LBB0_421
	v_mov_b32_e32 v9, v223
	s_and_b32 s4, s10, 0x7fc0
	s_addk_i32 s4, 0xaf00
	v_lshlrev_b32_e32 v0, 2, v9
	s_and_b32 s6, s9, 0x3c0
	v_and_b32_e32 v10, 60, v0
	v_ashrrev_i32_e32 v11, 4, v9
	v_or_b32_e32 v0, s6, v10
	v_readlane_b32 s0, v249, 10
	v_add_u32_e32 v6, s4, v11
	v_lshlrev_b32_e32 v176, 2, v0
	v_readlane_b32 s1, v249, 11
	v_ashrrev_i32_e32 v7, 31, v6
	v_lshlrev_b64 v[0:1], 12, v[6:7]
	v_lshl_add_u64 v[4:5], s[0:1], 0, v[176:177]
	v_add_u32_e32 v6, 32, v6
	v_lshl_add_u64 v[0:1], v[4:5], 0, v[0:1]
	v_ashrrev_i32_e32 v7, 31, v6
	global_load_dwordx4 v[0:3], v[0:1], off
	v_lshlrev_b64 v[6:7], 12, v[6:7]
	v_lshl_add_u64 v[4:5], v[4:5], 0, v[6:7]
	global_load_dwordx4 v[4:7], v[4:5], off
	v_ashrrev_i32_e32 v8, 3, v9
	v_lshlrev_b32_e32 v9, 3, v9
	s_movk_i32 s0, 0x104
	v_and_b32_e32 v12, 56, v9
	s_and_b32 s6, s10, 48
	s_lshr_b32 s4, s4, 6
	v_mul_lo_u32 v11, v11, s0
	v_lshlrev_b32_e32 v13, 2, v8
	v_lshlrev_b32_e32 v10, 2, v10
	v_mul_u32_u24_e32 v14, 0x104, v12
	s_add_i32 s4, s4, s6
	v_add3_u32 v10, 0, v10, v11
	v_add3_u32 v11, 0, v14, v13
	s_and_b32 s12, s9, 0xc0
	s_lshl_b64 s[6:7], s[4:5], 8
	v_add_u32_e32 v13, 0x2080, v10
	v_add_u32_e32 v14, 0x2088, v10
	v_add_u32_e32 v15, 0x400, v11
	v_ashrrev_i32_e32 v9, 31, v8
	s_or_b32 s6, s6, s12
	v_lshl_add_u64 v[8:9], s[6:7], 0, v[8:9]
	v_readlane_b32 s6, v250, 50
	v_and_b32_e32 v246, 0xff, v8
	v_lshlrev_b32_e32 v246, 6, v246
	v_and_b32_e32 v8, 0xffffff00, v8
	v_lshlrev_b64 v[8:9], 7, v[8:9]
	v_or_b32_e32 v8, v8, v246
	v_readlane_b32 s7, v250, 51
	v_lshlrev_b32_e32 v176, 1, v12
	v_and_b32_e32 v245, 64, v176
	v_and_b32_e32 v176, 48, v176
	v_lshl_or_b32 v176, v245, 8, v176
	s_waitcnt vmcnt(1)
	ds_write2_b32 v10, v0, v1 offset1:1
	ds_write2_b32 v10, v2, v3 offset0:2 offset1:3
	s_waitcnt vmcnt(0)
	ds_write2_b32 v13, v4, v5 offset1:1
	ds_write2_b32 v14, v6, v7 offset1:1
	s_waitcnt lgkmcnt(0)
	s_barrier
	ds_read2_b32 v[0:1], v11 offset1:65
	ds_read2_b32 v[2:3], v11 offset0:130 offset1:195
	ds_read2_b32 v[4:5], v15 offset0:4 offset1:69
	ds_read2_b32 v[6:7], v15 offset0:134 offset1:199
	v_lshl_add_u64 v[8:9], s[6:7], 0, v[8:9]
	v_lshl_add_u64 v[8:9], v[8:9], 0, v[176:177]
	s_waitcnt lgkmcnt(3)
	v_cvt_pk_bf16_f32 v0, v0, v1
	s_waitcnt lgkmcnt(2)
	v_cvt_pk_bf16_f32 v1, v2, v3
	s_waitcnt lgkmcnt(1)
	v_cvt_pk_bf16_f32 v2, v4, v5
	s_waitcnt lgkmcnt(0)
	v_cvt_pk_bf16_f32 v3, v6, v7
	global_store_dwordx4 v[8:9], v[0:3], off
	s_barrier

; DI unsigned pk_bf16(float a, float b) { bf2_t v = __builtin_convertvector((f2_t){a, b}, bf2_t); return __builtin_bit_cast(unsigned, v); }
; DI void transpose_tile(const float* __restrict__ src, int Nsrc, int K, bf16_t* __restrict__ dst, int mode, int k0, int n0, float* tile  ) {
;     ...
;     __syncthreads();
;     const int n = tid >> 3, ks = (tid & 7) * 8;
;     u32x4 w;
;     w.x = pk_bf16(tile[(ks + 0) * 65 + n], tile[(ks + 1) * 65 + n]);
;     w.y = pk_bf16(tile[(ks + 2) * 65 + n], tile[(ks + 3) * 65 + n]);
;     w.z = pk_bf16(tile[(ks + 4) * 65 + n], tile[(ks + 5) * 65 + n]);
;     w.w = pk_bf16(tile[(ks + 6) * 65 + n], tile[(ks + 7) * 65 + n]);
;     *(u32x4*)(dst + ((size_t)((n0 >> 8) * (K >> 6) + (k0 >> 6)) * 256 + (n0 & 255) + n) * 64 + ks) = w;
;     __syncthreads();
.LBB0_433:
	s_or_b64 exec, exec, s[6:7]
	v_add_u32_e32 v4, 0x2080, v10
	s_waitcnt vmcnt(0)
	ds_write2_b32 v4, v0, v1 offset1:1
	v_add_u32_e32 v0, 0x2088, v10
	ds_write2_b32 v0, v2, v3 offset1:1
	v_lshlrev_b32_e32 v0, 3, v8
	v_ashrrev_i32_e32 v4, 3, v8
	v_and_b32_e32 v10, 56, v0
	v_mul_u32_u24_e32 v0, 0x104, v10
	v_lshlrev_b32_e32 v1, 2, v4
	s_lshr_b32 s6, s4, 4
	v_add3_u32 v5, 0, v0, v1
	s_and_b32 s6, s6, 0xf0
	s_waitcnt lgkmcnt(0)
	s_barrier
	ds_read2_b32 v[0:1], v5 offset1:65
	ds_read2_b32 v[2:3], v5 offset0:130 offset1:195
	v_add_u32_e32 v5, 0x400, v5
	s_add_i32 s6, s6, s12
	ds_read2_b32 v[6:7], v5 offset0:4 offset1:69
	ds_read2_b32 v[8:9], v5 offset0:134 offset1:199
	s_lshl_b32 s6, s6, 8
	s_and_b32 s4, s4, 0xc0
	s_or_b32 s4, s6, s4
	v_ashrrev_i32_e32 v5, 31, v4
	v_lshl_add_u64 v[4:5], v[4:5], 0, s[4:5]
	v_readlane_b32 s6, v250, 52
	v_and_b32_e32 v246, 0xff, v4
	v_lshlrev_b32_e32 v246, 6, v246
	v_and_b32_e32 v4, 0xffffff00, v4
	v_lshlrev_b64 v[4:5], 7, v[4:5]
	v_or_b32_e32 v4, v4, v246
	v_readlane_b32 s7, v250, 53
	v_lshlrev_b32_e32 v176, 1, v10
	v_and_b32_e32 v245, 64, v176
	v_and_b32_e32 v176, 48, v176
	v_lshl_or_b32 v176, v245, 8, v176
	s_waitcnt lgkmcnt(3)
	v_cvt_pk_bf16_f32 v0, v0, v1
	v_lshl_add_u64 v[4:5], s[6:7], 0, v[4:5]
	s_waitcnt lgkmcnt(2)
	v_cvt_pk_bf16_f32 v1, v2, v3
	s_waitcnt lgkmcnt(1)
	v_cvt_pk_bf16_f32 v2, v6, v7
	s_waitcnt lgkmcnt(0)
	v_cvt_pk_bf16_f32 v3, v8, v9
	v_lshl_add_u64 v[4:5], v[4:5], 0, v[176:177]
	global_store_dwordx4 v[4:5], v[0:3], off
	s_barrier

; DI unsigned pk_bf16(float a, float b) { bf2_t v = __builtin_convertvector((f2_t){a, b}, bf2_t); return __builtin_bit_cast(unsigned, v); }
; DI int tid_() { int t = threadIdx.x; asm volatile("" : "+v"(t)); return t; }
; DI void transpose_tile(const float* __restrict__ src, int Nsrc, int K, bf16_t* __restrict__ dst, int mode, int k0, int n0, float* tile  ) {
;     const int tid = tid_();
;     const int n4 = (tid & 15) * 4;
;     const int c = colmap(mode, n0 + n4);
; #pragma unroll
;     for (int i = 0; i < 2; ++i) {
;         const int kk = (tid >> 4) + 32 * i;
;         f32x4 v = {0.f, 0.f, 0.f, 0.f};
;         if (c >= 0) v = *(const f32x4*)(src + (size_t)(k0 + kk) * Nsrc + c);
;         tile[kk * 65 + n4] = v[0]; tile[kk * 65 + n4 + 1] = v[1]; tile[kk * 65 + n4 + 2] = v[2]; tile[kk * 65 + n4 + 3] = v[3];
;     }
;     __syncthreads();
;     const int n = tid >> 3, ks = (tid & 7) * 8;
;     u32x4 w;
;     w.x = pk_bf16(tile[(ks + 0) * 65 + n], tile[(ks + 1) * 65 + n]);
;     w.y = pk_bf16(tile[(ks + 2) * 65 + n], tile[(ks + 3) * 65 + n]);
;     w.z = pk_bf16(tile[(ks + 4) * 65 + n], tile[(ks + 5) * 65 + n]);
;     w.w = pk_bf16(tile[(ks + 6) * 65 + n], tile[(ks + 7) * 65 + n]);
;     *(u32x4*)(dst + ((size_t)((n0 >> 8) * (K >> 6) + (k0 >> 6)) * 256 + (n0 & 255) + n) * 64 + ks) = w;
;     __syncthreads();
; DI void prep_weights(const Params& P, unsigned char* smem, int L, int vb, int nvb, int part  ) {
;     ...
;         else if (idx < E2) { const int q = idx - E1; const int j = L * 2 + q / T_W2, t = q % T_W2; const int kt = t / 16, nt = t % 16;
;             transpose_tile(P.ffn_w_out + (size_t)j * DFF * D, D, DFF, (bf16_t*)(ws + OFF_W2 + j * SZ_W2), 0, kt * 64, nt * 64, tile); }
.LBB0_435:
	s_andn2_b64 vcc, exec, s[6:7]
	s_cbranch_vccnz .LBB0_437
	s_add_i32 s4, s11, 0xfffff500
	s_cmpk_gt_u32 s4, 0x2bf
	s_cselect_b64 s[6:7], -1, 0
	v_cndmask_b32_e64 v0, 0, 1, s[6:7]
	v_readlane_b32 s16, v249, 53
	v_readfirstlane_b32 s6, v0
	s_or_b32 s12, s6, 2
	s_add_i32 s6, s11, 0xfffff240
	s_cmpk_lt_u32 s4, 0x2c0
	s_cselect_b32 s4, s4, s6
	s_mul_i32 s6, s12, 0xb00000
	v_readlane_b32 s26, v249, 63
	v_readlane_b32 s27, v248, 0
	s_add_u32 s6, s26, s6
	s_addc_u32 s7, s27, 0
	s_mul_i32 s12, s12, 0x580000
	v_readlane_b32 s13, v250, 20
	s_add_u32 s12, s13, s12
	v_readlane_b32 s13, v250, 21
	v_mov_b32_e32 v9, v223
	s_addc_u32 s13, s13, 0
	s_lshl_b32 s14, s4, 2
	s_lshl_b32 s15, s4, 6
	s_and_b32 s14, s14, 0xfc0
	v_lshlrev_b32_e32 v0, 2, v9
	s_and_b32 s16, s15, 0x3c0
	v_and_b32_e32 v10, 60, v0
	v_ashrrev_i32_e32 v11, 4, v9
	v_or_b32_e32 v0, s16, v10
	v_add_u32_e32 v6, s14, v11
	v_lshlrev_b32_e32 v176, 2, v0
	v_ashrrev_i32_e32 v7, 31, v6
	v_lshl_add_u64 v[4:5], s[6:7], 0, v[176:177]
	v_lshlrev_b64 v[0:1], 12, v[6:7]
	v_add_u32_e32 v6, 32, v6
	v_lshl_add_u64 v[0:1], v[4:5], 0, v[0:1]
	v_ashrrev_i32_e32 v7, 31, v6
	global_load_dwordx4 v[0:3], v[0:1], off
	v_lshlrev_b64 v[6:7], 12, v[6:7]
	v_lshl_add_u64 v[4:5], v[4:5], 0, v[6:7]
	global_load_dwordx4 v[4:7], v[4:5], off
	v_ashrrev_i32_e32 v8, 3, v9
	v_lshlrev_b32_e32 v9, 3, v9
	s_movk_i32 s0, 0x104
	v_and_b32_e32 v12, 56, v9
	s_bfe_u32 s6, s15, 0x20008
	v_mul_lo_u32 v11, v11, s0
	v_lshlrev_b32_e32 v13, 2, v8
	v_lshlrev_b32_e32 v10, 2, v10
	v_mul_u32_u24_e32 v14, 0x104, v12
	s_bfe_u32 s4, s4, 0x60004
	s_mul_i32 s6, s6, 44
	v_add3_u32 v10, 0, v10, v11
	v_add3_u32 v11, 0, v14, v13
	s_add_i32 s6, s6, s4
	v_add_u32_e32 v13, 0x2080, v10
	v_add_u32_e32 v14, 0x2088, v10
	v_add_u32_e32 v15, 0x400, v11
	s_and_b32 s7, s15, 0xc0
	s_lshl_b32 s4, s6, 8
	v_ashrrev_i32_e32 v9, 31, v8
	s_or_b32 s4, s4, s7
	v_lshl_add_u64 v[8:9], v[8:9], 0, s[4:5]
	v_and_b32_e32 v246, 0xff, v8
	v_lshlrev_b32_e32 v246, 6, v246
	v_and_b32_e32 v8, 0xffffff00, v8
	v_lshlrev_b64 v[8:9], 7, v[8:9]
	v_or_b32_e32 v8, v8, v246
	v_lshlrev_b32_e32 v176, 1, v12
	v_and_b32_e32 v245, 64, v176
	v_and_b32_e32 v176, 48, v176
	v_lshl_or_b32 v176, v245, 8, v176
	v_lshl_add_u64 v[8:9], s[12:13], 0, v[8:9]
	v_lshl_add_u64 v[8:9], v[8:9], 0, v[176:177]
	v_readlane_b32 s17, v249, 54
	v_readlane_b32 s18, v249, 55
	v_readlane_b32 s19, v249, 56
	v_readlane_b32 s20, v249, 57
	v_readlane_b32 s21, v249, 58
	v_readlane_b32 s22, v249, 59
	v_readlane_b32 s23, v249, 60
	v_readlane_b32 s24, v249, 61
	v_readlane_b32 s25, v249, 62
	v_readlane_b32 s28, v248, 1
	v_readlane_b32 s29, v248, 2
	v_readlane_b32 s30, v248, 3
	v_readlane_b32 s31, v248, 4
	s_waitcnt vmcnt(1)
	ds_write2_b32 v10, v0, v1 offset1:1
	ds_write2_b32 v10, v2, v3 offset0:2 offset1:3
	s_waitcnt vmcnt(0)
	ds_write2_b32 v13, v4, v5 offset1:1
	ds_write2_b32 v14, v6, v7 offset1:1
	s_waitcnt lgkmcnt(0)
	s_barrier
	ds_read2_b32 v[0:1], v11 offset1:65
	ds_read2_b32 v[2:3], v11 offset0:130 offset1:195
	ds_read2_b32 v[4:5], v15 offset0:4 offset1:69
	ds_read2_b32 v[6:7], v15 offset0:134 offset1:199
	s_waitcnt lgkmcnt(3)
	v_cvt_pk_bf16_f32 v0, v0, v1
	s_waitcnt lgkmcnt(2)
	v_cvt_pk_bf16_f32 v1, v2, v3
	s_waitcnt lgkmcnt(1)
	v_cvt_pk_bf16_f32 v2, v4, v5
	s_waitcnt lgkmcnt(0)
	v_cvt_pk_bf16_f32 v3, v6, v7
	global_store_dwordx4 v[8:9], v[0:3], off
	s_barrier

; DI unsigned pk_bf16(float a, float b) { bf2_t v = __builtin_convertvector((f2_t){a, b}, bf2_t); return __builtin_bit_cast(unsigned, v); }
; DI void transpose_tile(const float* __restrict__ src, int Nsrc, int K, bf16_t* __restrict__ dst, int mode, int k0, int n0, float* tile  ) {
;     ...
;     __syncthreads();
;     const int n = tid >> 3, ks = (tid & 7) * 8;
;     u32x4 w;
;     w.x = pk_bf16(tile[(ks + 0) * 65 + n], tile[(ks + 1) * 65 + n]);
;     w.y = pk_bf16(tile[(ks + 2) * 65 + n], tile[(ks + 3) * 65 + n]);
;     w.z = pk_bf16(tile[(ks + 4) * 65 + n], tile[(ks + 5) * 65 + n]);
;     w.w = pk_bf16(tile[(ks + 6) * 65 + n], tile[(ks + 7) * 65 + n]);
;     *(u32x4*)(dst + ((size_t)((n0 >> 8) * (K >> 6) + (k0 >> 6)) * 256 + (n0 & 255) + n) * 64 + ks) = w;
;     __syncthreads();
.LBB0_469:
	s_or_b64 exec, exec, s[6:7]
	v_add_u32_e32 v4, 0x2080, v10
	s_waitcnt vmcnt(0)
	ds_write2_b32 v4, v0, v1 offset1:1
	v_add_u32_e32 v0, 0x2088, v10
	ds_write2_b32 v0, v2, v3 offset1:1
	v_lshlrev_b32_e32 v0, 3, v8
	v_ashrrev_i32_e32 v4, 3, v8
	v_and_b32_e32 v8, 56, v0
	v_mul_u32_u24_e32 v0, 0x104, v8
	v_lshlrev_b32_e32 v1, 2, v4
	s_mul_hi_i32 s7, s13, 0xb00000
	s_mul_i32 s13, s13, 0xb00000
	v_add3_u32 v5, 0, v0, v1
	s_add_u32 s6, s90, s13
	s_waitcnt lgkmcnt(0)
	s_barrier
	ds_read2_b32 v[0:1], v5 offset1:65
	ds_read2_b32 v[2:3], v5 offset0:130 offset1:195
	s_addc_u32 s7, s91, s7
	s_lshl_b32 s11, s11, 2
	s_and_b32 s11, s11, -16
	s_add_i32 s14, s11, s4
	v_add_u32_e32 v5, 0x400, v5
	s_ashr_i32 s15, s14, 31
	s_waitcnt lgkmcnt(1)
	v_cvt_pk_bf16_f32 v0, v0, v1
	s_waitcnt lgkmcnt(0)
	v_cvt_pk_bf16_f32 v1, v2, v3
	ds_read2_b32 v[2:3], v5 offset0:4 offset1:69
	ds_read2_b32 v[6:7], v5 offset0:134 offset1:199
	s_lshl_b64 s[14:15], s[14:15], 8
	s_and_b32 s4, s12, 0xc0
	s_or_b32 s14, s14, s4
	v_ashrrev_i32_e32 v5, 31, v4
	v_lshl_add_u64 v[4:5], s[14:15], 0, v[4:5]
	v_and_b32_e32 v246, 0xff, v4
	v_lshlrev_b32_e32 v246, 6, v246
	v_and_b32_e32 v4, 0xffffff00, v4
	v_lshlrev_b64 v[4:5], 7, v[4:5]
	v_or_b32_e32 v4, v4, v246
	v_lshl_add_u64 v[4:5], s[6:7], 0, v[4:5]
	v_lshlrev_b32_e32 v176, 1, v8
	v_and_b32_e32 v245, 64, v176
	v_and_b32_e32 v176, 48, v176
	v_lshl_or_b32 v176, v245, 8, v176
	s_waitcnt lgkmcnt(1)
	v_cvt_pk_bf16_f32 v2, v2, v3
	s_waitcnt lgkmcnt(0)
	v_cvt_pk_bf16_f32 v3, v6, v7
	v_lshl_add_u64 v[4:5], v[4:5], 0, v[176:177]
	global_store_dwordx4 v[4:5], v[0:3], off
	s_barrier

; DI unsigned pk_bf16(float a, float b) { bf2_t v = __builtin_convertvector((f2_t){a, b}, bf2_t); return __builtin_bit_cast(unsigned, v); }
; DI int tid_() { int t = threadIdx.x; asm volatile("" : "+v"(t)); return t; }
; DI void transpose_tile(const float* __restrict__ src, int Nsrc, int K, bf16_t* __restrict__ dst, int mode, int k0, int n0, float* tile  ) {
;     const int tid = tid_();
;     const int n4 = (tid & 15) * 4;
;     const int c = colmap(mode, n0 + n4);
; #pragma unroll
;     for (int i = 0; i < 2; ++i) {
;         const int kk = (tid >> 4) + 32 * i;
;         f32x4 v = {0.f, 0.f, 0.f, 0.f};
;         if (c >= 0) v = *(const f32x4*)(src + (size_t)(k0 + kk) * Nsrc + c);
;         tile[kk * 65 + n4] = v[0]; tile[kk * 65 + n4 + 1] = v[1]; tile[kk * 65 + n4 + 2] = v[2]; tile[kk * 65 + n4 + 3] = v[3];
;     }
;     __syncthreads();
;     const int n = tid >> 3, ks = (tid & 7) * 8;
;     u32x4 w;
;     w.x = pk_bf16(tile[(ks + 0) * 65 + n], tile[(ks + 1) * 65 + n]);
;     w.y = pk_bf16(tile[(ks + 2) * 65 + n], tile[(ks + 3) * 65 + n]);
;     w.z = pk_bf16(tile[(ks + 4) * 65 + n], tile[(ks + 5) * 65 + n]);
;     w.w = pk_bf16(tile[(ks + 6) * 65 + n], tile[(ks + 7) * 65 + n]);
;     *(u32x4*)(dst + ((size_t)((n0 >> 8) * (K >> 6) + (k0 >> 6)) * 256 + (n0 & 255) + n) * 64 + ks) = w;
;     __syncthreads();
; DI void prep_weights(const Params& P, unsigned char* smem, int L, int vb, int nvb, int part  ) {
;     ...
;         else if (idx < E5) { const int t = idx - E4; const int kt = t / 16, nt = t % 16;
;             transpose_tile(P.ple_w_gate + (size_t)L * D * D, D, D, (bf16_t*)(ws + OFF_WG + L * SZ_WSQ), 0, kt * 64, nt * 64, tile); }
;         else { const int t = idx - E5; const int kt = t / 16, nt = t % 16;
;             transpose_tile(P.ple_w_proj + (size_t)L * PLE * D, D, PLE, (bf16_t*)(ws + OFF_WP + L * SZ_WP), 0, kt * 64, nt * 64, tile); }
.LBB0_471:
	s_cmpk_gt_i32 s10, 0xaff
	s_mov_b64 s[6:7], -1
	s_cbranch_scc0 .LBB0_499
	s_cmpk_gt_u32 s10, 0x107f
	s_cbranch_scc0 .LBB0_496
	s_cmpk_gt_u32 s10, 0x143f
	s_cbranch_scc0 .LBB0_483
	s_cmpk_gt_u32 s10, 0x153f
	s_cbranch_scc0 .LBB0_480
	s_and_b32 s11, s9, 0x3c0
	s_cmpk_gt_u32 s10, 0x163f
	s_cbranch_scc0 .LBB0_477
	v_mov_b32_e32 v8, v223
	s_and_b32 s4, s8, 0x7fffffc0
	s_addk_i32 s4, 0xa700
	v_lshlrev_b32_e32 v0, 2, v8
	v_and_b32_e32 v0, 60, v0
	v_ashrrev_i32_e32 v9, 4, v8
	v_or_b32_e32 v1, s11, v0
	v_readlane_b32 s0, v250, 54
	v_add_u32_e32 v6, s4, v9
	v_lshlrev_b32_e32 v176, 2, v1
	v_readlane_b32 s1, v250, 55
	v_ashrrev_i32_e32 v7, 31, v6
	v_lshlrev_b32_e32 v10, 2, v0
	v_lshl_add_u64 v[4:5], s[0:1], 0, v[176:177]
	v_lshlrev_b64 v[0:1], 12, v[6:7]
	v_lshl_add_u64 v[0:1], v[4:5], 0, v[0:1]
	global_load_dwordx4 v[0:3], v[0:1], off
	s_movk_i32 s0, 0x104
	v_mul_lo_u32 v7, v9, s0
	v_add3_u32 v7, 0, v10, v7
	s_and_b32 s6, s10, 12
	s_lshr_b32 s4, s4, 6
	s_add_i32 s4, s4, s6
	s_lshl_b64 s[6:7], s[4:5], 8
	s_and_b32 s4, s9, 0xc0
	s_or_b32 s6, s6, s4
	s_waitcnt vmcnt(0)
	ds_write2_b32 v7, v0, v1 offset1:1
	ds_write2_b32 v7, v2, v3 offset0:2 offset1:3
	v_add_u32_e32 v0, 32, v6
	v_ashrrev_i32_e32 v1, 31, v0
	v_lshlrev_b64 v[0:1], 12, v[0:1]
	v_lshl_add_u64 v[0:1], v[4:5], 0, v[0:1]
	global_load_dwordx4 v[0:3], v[0:1], off
	v_add_u32_e32 v4, 0x2080, v7
	s_waitcnt vmcnt(0)
	ds_write2_b32 v4, v0, v1 offset1:1
	v_add_u32_e32 v0, 0x2088, v7
	ds_write2_b32 v0, v2, v3 offset1:1
	v_lshlrev_b32_e32 v0, 3, v8
	v_ashrrev_i32_e32 v4, 3, v8
	v_and_b32_e32 v8, 56, v0
	v_mul_u32_u24_e32 v0, 0x104, v8
	v_lshlrev_b32_e32 v1, 2, v4
	v_add3_u32 v5, 0, v0, v1
	s_waitcnt lgkmcnt(0)
	s_barrier
	ds_read2_b32 v[0:1], v5 offset1:65
	ds_read2_b32 v[2:3], v5 offset0:130 offset1:195
	v_add_u32_e32 v5, 0x400, v5
	ds_read2_b32 v[6:7], v5 offset0:134 offset1:199
	v_lshlrev_b32_e32 v176, 1, v8
	v_and_b32_e32 v245, 64, v176
	v_and_b32_e32 v176, 48, v176
	v_lshl_or_b32 v176, v245, 8, v176
	s_waitcnt lgkmcnt(2)
	v_cvt_pk_bf16_f32 v0, v0, v1
	s_waitcnt lgkmcnt(1)
	v_cvt_pk_bf16_f32 v1, v2, v3
	ds_read2_b32 v[2:3], v5 offset0:4 offset1:69
	v_ashrrev_i32_e32 v5, 31, v4
	v_lshl_add_u64 v[4:5], s[6:7], 0, v[4:5]
	v_readlane_b32 s6, v250, 46
	v_and_b32_e32 v246, 0xff, v4
	v_lshlrev_b32_e32 v246, 6, v246
	v_and_b32_e32 v4, 0xffffff00, v4
	v_lshlrev_b64 v[4:5], 7, v[4:5]
	v_or_b32_e32 v4, v4, v246
	v_readlane_b32 s7, v250, 47
	s_waitcnt lgkmcnt(0)
	v_cvt_pk_bf16_f32 v2, v2, v3
	v_cvt_pk_bf16_f32 v3, v6, v7
	v_lshl_add_u64 v[4:5], s[6:7], 0, v[4:5]
	v_lshl_add_u64 v[4:5], v[4:5], 0, v[176:177]
	global_store_dwordx4 v[4:5], v[0:3], off
	s_barrier
	s_mov_b64 s[6:7], 0
.LBB0_477:
	s_andn2_b64 vcc, exec, s[6:7]
	s_cbranch_vccnz .LBB0_479
	v_mov_b32_e32 v8, v223
	s_and_b32 s4, s8, 0x7fc0
	s_addk_i32 s4, 0xab00
	v_lshlrev_b32_e32 v0, 2, v8
	v_and_b32_e32 v0, 60, v0
	v_ashrrev_i32_e32 v9, 4, v8
	v_or_b32_e32 v1, s11, v0
	v_readlane_b32 s0, v250, 56
	v_add_u32_e32 v6, s4, v9
	v_lshlrev_b32_e32 v176, 2, v1
	v_readlane_b32 s1, v250, 57
	v_ashrrev_i32_e32 v7, 31, v6
	v_lshlrev_b32_e32 v10, 2, v0
	v_lshl_add_u64 v[4:5], s[0:1], 0, v[176:177]
	v_lshlrev_b64 v[0:1], 12, v[6:7]
	v_lshl_add_u64 v[0:1], v[4:5], 0, v[0:1]
	global_load_dwordx4 v[0:3], v[0:1], off
	s_movk_i32 s0, 0x104
	v_mul_lo_u32 v7, v9, s0
	v_add3_u32 v7, 0, v10, v7
	s_and_b32 s6, s8, 48
	s_lshr_b32 s4, s4, 6
	s_add_i32 s4, s4, s6
	s_lshl_b64 s[6:7], s[4:5], 8
	s_and_b32 s4, s9, 0xc0
	s_or_b32 s6, s6, s4
	s_waitcnt vmcnt(0)
	ds_write2_b32 v7, v0, v1 offset1:1
	ds_write2_b32 v7, v2, v3 offset0:2 offset1:3
	v_add_u32_e32 v0, 32, v6
	v_ashrrev_i32_e32 v1, 31, v0
	v_lshlrev_b64 v[0:1], 12, v[0:1]
	v_lshl_add_u64 v[0:1], v[4:5], 0, v[0:1]
	global_load_dwordx4 v[0:3], v[0:1], off
	v_add_u32_e32 v4, 0x2080, v7
	s_waitcnt vmcnt(0)
	ds_write2_b32 v4, v0, v1 offset1:1
	v_add_u32_e32 v0, 0x2088, v7
	ds_write2_b32 v0, v2, v3 offset1:1
	v_lshlrev_b32_e32 v0, 3, v8
	v_ashrrev_i32_e32 v4, 3, v8
	v_and_b32_e32 v8, 56, v0
	v_mul_u32_u24_e32 v0, 0x104, v8
	v_lshlrev_b32_e32 v1, 2, v4
	v_add3_u32 v5, 0, v0, v1
	s_waitcnt lgkmcnt(0)
	s_barrier
	ds_read2_b32 v[0:1], v5 offset1:65
	ds_read2_b32 v[2:3], v5 offset0:130 offset1:195
	v_add_u32_e32 v5, 0x400, v5
	ds_read2_b32 v[6:7], v5 offset0:134 offset1:199
	v_lshlrev_b32_e32 v176, 1, v8
	v_and_b32_e32 v245, 64, v176
	v_and_b32_e32 v176, 48, v176
	v_lshl_or_b32 v176, v245, 8, v176
	s_waitcnt lgkmcnt(2)
	v_cvt_pk_bf16_f32 v0, v0, v1
	s_waitcnt lgkmcnt(1)
	v_cvt_pk_bf16_f32 v1, v2, v3
	ds_read2_b32 v[2:3], v5 offset0:4 offset1:69
	v_ashrrev_i32_e32 v5, 31, v4
	v_lshl_add_u64 v[4:5], s[6:7], 0, v[4:5]
	v_readlane_b32 s6, v250, 48
	v_and_b32_e32 v246, 0xff, v4
	v_lshlrev_b32_e32 v246, 6, v246
	v_and_b32_e32 v4, 0xffffff00, v4
	v_lshlrev_b64 v[4:5], 7, v[4:5]
	v_or_b32_e32 v4, v4, v246
	v_readlane_b32 s7, v250, 49
	s_waitcnt lgkmcnt(0)
	v_cvt_pk_bf16_f32 v2, v2, v3
	v_cvt_pk_bf16_f32 v3, v6, v7
	v_lshl_add_u64 v[4:5], s[6:7], 0, v[4:5]
	v_lshl_add_u64 v[4:5], v[4:5], 0, v[176:177]
	global_store_dwordx4 v[4:5], v[0:3], off
	s_barrier

; DI unsigned pk_bf16(float a, float b) { bf2_t v = __builtin_convertvector((f2_t){a, b}, bf2_t); return __builtin_bit_cast(unsigned, v); }
; DI int tid_() { int t = threadIdx.x; asm volatile("" : "+v"(t)); return t; }
; DI void transpose_tile(const float* __restrict__ src, int Nsrc, int K, bf16_t* __restrict__ dst, int mode, int k0, int n0, float* tile  ) {
;     const int tid = tid_();
;     const int n4 = (tid & 15) * 4;
;     const int c = colmap(mode, n0 + n4);
; #pragma unroll
;     for (int i = 0; i < 2; ++i) {
;         const int kk = (tid >> 4) + 32 * i;
;         f32x4 v = {0.f, 0.f, 0.f, 0.f};
;         if (c >= 0) v = *(const f32x4*)(src + (size_t)(k0 + kk) * Nsrc + c);
;         tile[kk * 65 + n4] = v[0]; tile[kk * 65 + n4 + 1] = v[1]; tile[kk * 65 + n4 + 2] = v[2]; tile[kk * 65 + n4 + 3] = v[3];
;     }
;     __syncthreads();
;     const int n = tid >> 3, ks = (tid & 7) * 8;
;     u32x4 w;
;     w.x = pk_bf16(tile[(ks + 0) * 65 + n], tile[(ks + 1) * 65 + n]);
;     w.y = pk_bf16(tile[(ks + 2) * 65 + n], tile[(ks + 3) * 65 + n]);
;     w.z = pk_bf16(tile[(ks + 4) * 65 + n], tile[(ks + 5) * 65 + n]);
;     w.w = pk_bf16(tile[(ks + 6) * 65 + n], tile[(ks + 7) * 65 + n]);
;     *(u32x4*)(dst + ((size_t)((n0 >> 8) * (K >> 6) + (k0 >> 6)) * 256 + (n0 & 255) + n) * 64 + ks) = w;
;     __syncthreads();
; DI void prep_weights(const Params& P, unsigned char* smem, int L, int vb, int nvb, int part  ) {
;     ...
;         else if (idx < E4) { const int t = idx - E3; const int kt = t / 16, nt = t % 16;
;             transpose_tile(P.mix_w_out + (size_t)L * D * D, D, D, (bf16_t*)(ws + OFF_WOUT + L * SZ_WSQ), 0, kt * 64, nt * 64, tile); }
.LBB0_480:
	s_andn2_b64 vcc, exec, s[6:7]
	s_cbranch_vccnz .LBB0_482
	v_mov_b32_e32 v8, v223
	s_and_b32 s4, s8, 0x7fc0
	s_addk_i32 s4, 0xaf00
	v_lshlrev_b32_e32 v0, 2, v8
	s_and_b32 s6, s9, 0x3c0
	v_and_b32_e32 v0, 60, v0
	v_ashrrev_i32_e32 v9, 4, v8
	v_or_b32_e32 v1, s6, v0
	v_readlane_b32 s0, v249, 10
	v_add_u32_e32 v6, s4, v9
	v_lshlrev_b32_e32 v176, 2, v1
	v_readlane_b32 s1, v249, 11
	v_ashrrev_i32_e32 v7, 31, v6
	v_lshlrev_b32_e32 v10, 2, v0
	v_lshl_add_u64 v[4:5], s[0:1], 0, v[176:177]
	v_lshlrev_b64 v[0:1], 12, v[6:7]
	v_lshl_add_u64 v[0:1], v[4:5], 0, v[0:1]
	global_load_dwordx4 v[0:3], v[0:1], off
	s_movk_i32 s0, 0x104
	v_mul_lo_u32 v7, v9, s0
	v_add3_u32 v7, 0, v10, v7
	s_and_b32 s6, s8, 48
	s_lshr_b32 s4, s4, 6
	s_add_i32 s4, s4, s6
	s_lshl_b64 s[6:7], s[4:5], 8
	s_and_b32 s4, s9, 0xc0
	s_or_b32 s6, s6, s4
	s_waitcnt vmcnt(0)
	ds_write2_b32 v7, v0, v1 offset1:1
	ds_write2_b32 v7, v2, v3 offset0:2 offset1:3
	v_add_u32_e32 v0, 32, v6
	v_ashrrev_i32_e32 v1, 31, v0
	v_lshlrev_b64 v[0:1], 12, v[0:1]
	v_lshl_add_u64 v[0:1], v[4:5], 0, v[0:1]
	global_load_dwordx4 v[0:3], v[0:1], off
	v_add_u32_e32 v4, 0x2080, v7
	s_waitcnt vmcnt(0)
	ds_write2_b32 v4, v0, v1 offset1:1
	v_add_u32_e32 v0, 0x2088, v7
	ds_write2_b32 v0, v2, v3 offset1:1
	v_lshlrev_b32_e32 v0, 3, v8
	v_ashrrev_i32_e32 v4, 3, v8
	v_and_b32_e32 v8, 56, v0
	v_mul_u32_u24_e32 v0, 0x104, v8
	v_lshlrev_b32_e32 v1, 2, v4
	v_add3_u32 v5, 0, v0, v1
	s_waitcnt lgkmcnt(0)
	s_barrier
	ds_read2_b32 v[0:1], v5 offset1:65
	ds_read2_b32 v[2:3], v5 offset0:130 offset1:195
	v_add_u32_e32 v5, 0x400, v5
	ds_read2_b32 v[6:7], v5 offset0:134 offset1:199
	v_lshlrev_b32_e32 v176, 1, v8
	v_and_b32_e32 v245, 64, v176
	v_and_b32_e32 v176, 48, v176
	v_lshl_or_b32 v176, v245, 8, v176
	s_waitcnt lgkmcnt(2)
	v_cvt_pk_bf16_f32 v0, v0, v1
	s_waitcnt lgkmcnt(1)
	v_cvt_pk_bf16_f32 v1, v2, v3
	ds_read2_b32 v[2:3], v5 offset0:4 offset1:69
	v_ashrrev_i32_e32 v5, 31, v4
	v_lshl_add_u64 v[4:5], s[6:7], 0, v[4:5]
	v_readlane_b32 s6, v250, 50
	v_and_b32_e32 v246, 0xff, v4
	v_lshlrev_b32_e32 v246, 6, v246
	v_and_b32_e32 v4, 0xffffff00, v4
	v_lshlrev_b64 v[4:5], 7, v[4:5]
	v_or_b32_e32 v4, v4, v246
	v_readlane_b32 s7, v250, 51
	s_waitcnt lgkmcnt(0)
	v_cvt_pk_bf16_f32 v2, v2, v3
	v_cvt_pk_bf16_f32 v3, v6, v7
	v_lshl_add_u64 v[4:5], s[6:7], 0, v[4:5]
	v_lshl_add_u64 v[4:5], v[4:5], 0, v[176:177]
	global_store_dwordx4 v[4:5], v[0:3], off
	s_barrier

; DI unsigned pk_bf16(float a, float b) { bf2_t v = __builtin_convertvector((f2_t){a, b}, bf2_t); return __builtin_bit_cast(unsigned, v); }
; DI void transpose_tile(const float* __restrict__ src, int Nsrc, int K, bf16_t* __restrict__ dst, int mode, int k0, int n0, float* tile  ) {
;     ...
;     __syncthreads();
;     const int n = tid >> 3, ks = (tid & 7) * 8;
;     u32x4 w;
;     w.x = pk_bf16(tile[(ks + 0) * 65 + n], tile[(ks + 1) * 65 + n]);
;     w.y = pk_bf16(tile[(ks + 2) * 65 + n], tile[(ks + 3) * 65 + n]);
;     w.z = pk_bf16(tile[(ks + 4) * 65 + n], tile[(ks + 5) * 65 + n]);
;     w.w = pk_bf16(tile[(ks + 6) * 65 + n], tile[(ks + 7) * 65 + n]);
;     *(u32x4*)(dst + ((size_t)((n0 >> 8) * (K >> 6) + (k0 >> 6)) * 256 + (n0 & 255) + n) * 64 + ks) = w;
;     __syncthreads();
.LBB0_494:
	s_or_b64 exec, exec, s[6:7]
	v_add_u32_e32 v4, 0x2080, v10
	s_waitcnt vmcnt(0)
	ds_write2_b32 v4, v0, v1 offset1:1
	v_add_u32_e32 v0, 0x2088, v10
	ds_write2_b32 v0, v2, v3 offset1:1
	v_lshlrev_b32_e32 v0, 3, v8
	v_ashrrev_i32_e32 v4, 3, v8
	v_and_b32_e32 v8, 56, v0
	v_mul_u32_u24_e32 v0, 0x104, v8
	v_lshlrev_b32_e32 v1, 2, v4
	v_add3_u32 v5, 0, v0, v1
	s_waitcnt lgkmcnt(0)
	s_barrier
	ds_read2_b32 v[0:1], v5 offset1:65
	ds_read2_b32 v[2:3], v5 offset0:130 offset1:195
	s_lshr_b32 s6, s4, 4
	s_and_b32 s6, s6, 0xf0
	v_add_u32_e32 v5, 0x400, v5
	s_add_i32 s6, s6, s11
	s_waitcnt lgkmcnt(1)
	v_cvt_pk_bf16_f32 v0, v0, v1
	s_waitcnt lgkmcnt(0)
	v_cvt_pk_bf16_f32 v1, v2, v3
	ds_read2_b32 v[2:3], v5 offset0:4 offset1:69
	ds_read2_b32 v[6:7], v5 offset0:134 offset1:199
	s_lshl_b32 s6, s6, 8
	s_and_b32 s4, s4, 0xc0
	s_or_b32 s4, s6, s4
	v_ashrrev_i32_e32 v5, 31, v4
	v_lshl_add_u64 v[4:5], v[4:5], 0, s[4:5]
	v_readlane_b32 s6, v250, 52
	v_and_b32_e32 v246, 0xff, v4
	v_lshlrev_b32_e32 v246, 6, v246
	v_and_b32_e32 v4, 0xffffff00, v4
	v_lshlrev_b64 v[4:5], 7, v[4:5]
	v_or_b32_e32 v4, v4, v246
	v_readlane_b32 s7, v250, 53
	v_lshlrev_b32_e32 v176, 1, v8
	v_and_b32_e32 v245, 64, v176
	v_and_b32_e32 v176, 48, v176
	v_lshl_or_b32 v176, v245, 8, v176
	s_waitcnt lgkmcnt(1)
	v_cvt_pk_bf16_f32 v2, v2, v3
	v_lshl_add_u64 v[4:5], s[6:7], 0, v[4:5]
	s_waitcnt lgkmcnt(0)
	v_cvt_pk_bf16_f32 v3, v6, v7
	v_lshl_add_u64 v[4:5], v[4:5], 0, v[176:177]
	global_store_dwordx4 v[4:5], v[0:3], off
	s_barrier

; DI unsigned pk_bf16(float a, float b) { bf2_t v = __builtin_convertvector((f2_t){a, b}, bf2_t); return __builtin_bit_cast(unsigned, v); }
; DI int tid_() { int t = threadIdx.x; asm volatile("" : "+v"(t)); return t; }
; DI void transpose_tile(const float* __restrict__ src, int Nsrc, int K, bf16_t* __restrict__ dst, int mode, int k0, int n0, float* tile  ) {
;     const int tid = tid_();
;     const int n4 = (tid & 15) * 4;
;     const int c = colmap(mode, n0 + n4);
; #pragma unroll
;     for (int i = 0; i < 2; ++i) {
;         const int kk = (tid >> 4) + 32 * i;
;         f32x4 v = {0.f, 0.f, 0.f, 0.f};
;         if (c >= 0) v = *(const f32x4*)(src + (size_t)(k0 + kk) * Nsrc + c);
;         tile[kk * 65 + n4] = v[0]; tile[kk * 65 + n4 + 1] = v[1]; tile[kk * 65 + n4 + 2] = v[2]; tile[kk * 65 + n4 + 3] = v[3];
;     }
;     __syncthreads();
;     const int n = tid >> 3, ks = (tid & 7) * 8;
;     u32x4 w;
;     w.x = pk_bf16(tile[(ks + 0) * 65 + n], tile[(ks + 1) * 65 + n]);
;     w.y = pk_bf16(tile[(ks + 2) * 65 + n], tile[(ks + 3) * 65 + n]);
;     w.z = pk_bf16(tile[(ks + 4) * 65 + n], tile[(ks + 5) * 65 + n]);
;     w.w = pk_bf16(tile[(ks + 6) * 65 + n], tile[(ks + 7) * 65 + n]);
;     *(u32x4*)(dst + ((size_t)((n0 >> 8) * (K >> 6) + (k0 >> 6)) * 256 + (n0 & 255) + n) * 64 + ks) = w;
;     __syncthreads();
; DI void prep_weights(const Params& P, unsigned char* smem, int L, int vb, int nvb, int part  ) {
;     ...
;         else if (idx < E2) { const int q = idx - E1; const int j = L * 2 + q / T_W2, t = q % T_W2; const int kt = t / 16, nt = t % 16;
;             transpose_tile(P.ffn_w_out + (size_t)j * DFF * D, D, DFF, (bf16_t*)(ws + OFF_W2 + j * SZ_W2), 0, kt * 64, nt * 64, tile); }
.LBB0_496:
	s_andn2_b64 vcc, exec, s[6:7]
	s_cbranch_vccnz .LBB0_498
	s_add_i32 s4, s10, 0xfffff500
	s_cmpk_gt_u32 s4, 0x2bf
	s_cselect_b64 s[6:7], -1, 0
	v_cndmask_b32_e64 v0, 0, 1, s[6:7]
	s_add_i32 s7, s10, 0xfffff240
	v_readfirstlane_b32 s6, v0
	s_or_b32 s6, s6, 2
	s_cmpk_lt_u32 s4, 0x2c0
	v_readlane_b32 s12, v249, 53
	s_cselect_b32 s4, s4, s7
	s_mul_i32 s7, s6, 0xb00000
	v_readlane_b32 s22, v249, 63
	v_readlane_b32 s13, v249, 54
	v_readlane_b32 s23, v248, 0
	s_add_u32 s12, s22, s7
	s_addc_u32 s13, s23, 0
	s_mul_i32 s6, s6, 0x580000
	v_readlane_b32 s7, v250, 20
	v_readlane_b32 s14, v249, 55
	s_add_u32 s6, s7, s6
	v_readlane_b32 s7, v250, 21
	v_mov_b32_e32 v8, v223
	v_readlane_b32 s15, v249, 56
	s_addc_u32 s7, s7, 0
	s_lshl_b32 s11, s4, 2
	s_lshl_b32 s14, s4, 6
	s_and_b32 s11, s11, 0xfc0
	v_lshlrev_b32_e32 v0, 2, v8
	s_and_b32 s15, s14, 0x3c0
	v_and_b32_e32 v0, 60, v0
	v_ashrrev_i32_e32 v9, 4, v8
	v_or_b32_e32 v1, s15, v0
	v_add_u32_e32 v6, s11, v9
	v_lshlrev_b32_e32 v176, 2, v1
	v_ashrrev_i32_e32 v7, 31, v6
	v_lshlrev_b32_e32 v10, 2, v0
	v_lshl_add_u64 v[4:5], s[12:13], 0, v[176:177]
	v_lshlrev_b64 v[0:1], 12, v[6:7]
	v_lshl_add_u64 v[0:1], v[4:5], 0, v[0:1]
	global_load_dwordx4 v[0:3], v[0:1], off
	s_movk_i32 s0, 0x104
	v_mul_lo_u32 v7, v9, s0
	v_add3_u32 v7, 0, v10, v7
	s_bfe_u32 s11, s14, 0x20008
	s_mul_i32 s11, s11, 44
	s_bfe_u32 s4, s4, 0x60004
	s_add_i32 s11, s11, s4
	s_lshl_b32 s4, s11, 8
	s_and_b32 s11, s14, 0xc0
	s_or_b32 s4, s4, s11
	v_readlane_b32 s16, v249, 57
	v_readlane_b32 s17, v249, 58
	v_readlane_b32 s18, v249, 59
	v_readlane_b32 s19, v249, 60
	v_readlane_b32 s20, v249, 61
	v_readlane_b32 s21, v249, 62
	v_readlane_b32 s24, v248, 1
	v_readlane_b32 s25, v248, 2
	v_readlane_b32 s26, v248, 3
	v_readlane_b32 s27, v248, 4
	s_waitcnt vmcnt(0)
	ds_write2_b32 v7, v0, v1 offset1:1
	ds_write2_b32 v7, v2, v3 offset0:2 offset1:3
	v_add_u32_e32 v0, 32, v6
	v_ashrrev_i32_e32 v1, 31, v0
	v_lshlrev_b64 v[0:1], 12, v[0:1]
	v_lshl_add_u64 v[0:1], v[4:5], 0, v[0:1]
	global_load_dwordx4 v[0:3], v[0:1], off
	v_add_u32_e32 v4, 0x2080, v7
	s_waitcnt vmcnt(0)
	ds_write2_b32 v4, v0, v1 offset1:1
	v_add_u32_e32 v0, 0x2088, v7
	ds_write2_b32 v0, v2, v3 offset1:1
	v_lshlrev_b32_e32 v0, 3, v8
	v_ashrrev_i32_e32 v4, 3, v8
	v_and_b32_e32 v8, 56, v0
	v_mul_u32_u24_e32 v0, 0x104, v8
	v_lshlrev_b32_e32 v1, 2, v4
	v_add3_u32 v5, 0, v0, v1
	s_waitcnt lgkmcnt(0)
	s_barrier
	ds_read2_b32 v[0:1], v5 offset1:65
	ds_read2_b32 v[2:3], v5 offset0:130 offset1:195
	v_add_u32_e32 v5, 0x400, v5
	ds_read2_b32 v[6:7], v5 offset0:134 offset1:199
	v_lshlrev_b32_e32 v176, 1, v8
	v_and_b32_e32 v245, 64, v176
	v_and_b32_e32 v176, 48, v176
	v_lshl_or_b32 v176, v245, 8, v176
	s_waitcnt lgkmcnt(2)
	v_cvt_pk_bf16_f32 v0, v0, v1
	s_waitcnt lgkmcnt(1)
	v_cvt_pk_bf16_f32 v1, v2, v3
	ds_read2_b32 v[2:3], v5 offset0:4 offset1:69
	v_ashrrev_i32_e32 v5, 31, v4
	v_lshl_add_u64 v[4:5], v[4:5], 0, s[4:5]
	v_and_b32_e32 v246, 0xff, v4
	v_lshlrev_b32_e32 v246, 6, v246
	v_and_b32_e32 v4, 0xffffff00, v4
	v_lshlrev_b64 v[4:5], 7, v[4:5]
	v_or_b32_e32 v4, v4, v246
	v_lshl_add_u64 v[4:5], s[6:7], 0, v[4:5]
	s_waitcnt lgkmcnt(0)
	v_cvt_pk_bf16_f32 v2, v2, v3
	v_cvt_pk_bf16_f32 v3, v6, v7
	v_lshl_add_u64 v[4:5], v[4:5], 0, v[176:177]
	global_store_dwordx4 v[4:5], v[0:3], off
	s_barrier
